# gla_out item: second V half-tile, both gate rows and head-norm gains requested early (fewer serialized global round trips); otherwise as previous
# speedup vs baseline: 1.0012x; 1.0012x over previous
; __device__ __forceinline__ void gla_load_vt(unsigned char* lds, const bf16_t* cv_t0  ) {
;     bf16_t* Vt = (bf16_t*)(lds + GL_VT);
;     int tid_ = threadIdx.x; asm volatile("" : "+v"(tid_)); const int tid = tid_;
; #pragma unroll
;     for (int r = 0; r < 2; ++r) { const int ci = tid + 512 * r, s = ci & 63, eg = ci >> 6;
;         const u32x4 w = *(const u32x4*)(cv_t0 + (size_t)s * 512 + eg * 8);
;         bf16_t* dst = Vt + (eg * 8) * 72 + s;
;         dst[0 * 72] = (bf16_t)(w.x & 0xffffu); dst[1 * 72] = (bf16_t)(w.x >> 16); dst[2 * 72] = (bf16_t)(w.y & 0xffffu); dst[3 * 72] = (bf16_t)(w.y >> 16);
;         dst[4 * 72] = (bf16_t)(w.z & 0xffffu); dst[5 * 72] = (bf16_t)(w.z >> 16); dst[6 * 72] = (bf16_t)(w.w & 0xffffu); dst[7 * 72] = (bf16_t)(w.w >> 16); }
; __device__ __forceinline__ void gla_out_item(unsigned char* lds, unsigned char* ws, const float* wgate, const float* bgate, const float* hnorm, int l, int item, bool dowrite = true) {
;     const int c = item % 132, h = (item / 132) & 3, b = item / 528;
;     const int t0 = b * TB + c * 64;
;     int tid_ = threadIdx.x; asm volatile("" : "+v"(tid_));
;     const int tid = tid_, lane = tid & 63, wid = tid >> 6, ql = lane & 15, g = lane >> 4;
;     const float* Bs = (const float*)(lds + GL_BS);
;     bf16_t* QE = (bf16_t*)(lds + GL_QE); bf16_t* KE = (bf16_t*)(lds + GL_KE); bf16_t* ATT = (bf16_t*)(lds + GL_ATT); const bf16_t* Vt = (const bf16_t*)(lds + GL_VT);
;     const u32x4 qraw = *(const u32x4*)((const bf16_t*)(ws + O_CQ) + (size_t)(t0 + (tid >> 3)) * 256 + h * 64 + (tid & 7) * 8);
;     const u32x4 kraw = *(const u32x4*)((const bf16_t*)(ws + O_CK) + (size_t)(t0 + (tid >> 3)) * 256 + h * 64 + (tid & 7) * 8);
;     bf16x8 sfr[2][2];
; #pragma unroll
;     for (int dd = 0; dd < 2; ++dd)
; #pragma unroll
;         for (int kk = 0; kk < 2; ++kk) sfr[dd][kk] = *(const bf16x8*)((const bf16_t*)(ws + O_ST) + (size_t)(((b * 4 + h) * 2 + dd) * 132 + c) * 8192 + (wid * 16 + ql) * 64 + kk * 32 + g * 8);
;     const u32x4 rraw0 = *(const u32x4*)((const bf16_t*)(ws + O_CR) + (size_t)(t0 + (tid >> 3)) * 512 + h * 128 + (tid & 7) * 16);
;     const u32x4 rraw1 = *(const u32x4*)((const bf16_t*)(ws + O_CR) + (size_t)(t0 + (tid >> 3)) * 512 + h * 128 + (tid & 7) * 16 + 8);
;     gla_load_vt(lds, (const bf16_t*)(ws + O_CV) + (size_t)t0 * 512 + h * 128);
.Lgo_map:
	s_lshl_b32 s37, s51, 6
	s_mul_hi_i32 s0, s51, 0x3e0f83e1
	s_ashr_i32 s1, s0, 5
	s_lshr_b32 s18, s0, 31
	s_ashr_i32 s0, s0, 7
	s_add_i32 s1, s1, s18
	s_add_i32 s18, s0, s18
	s_waitcnt vmcnt(0)
	v_mov_b32_e32 v68, v203
	s_mul_i32 s38, s18, 0x2100
	s_mul_i32 s19, s1, 0x84
	v_ashrrev_i32_e32 v37, 3, v68
	s_and_b32 s52, s1, 3
	s_mulk_i32 s1, 0x2100
	v_add_u32_e32 v0, s38, v37
	v_subrev_u32_e32 v0, s1, v0
	v_add_u32_e32 v0, s37, v0
	v_ashrrev_i32_e32 v1, 31, v0
	v_lshlrev_b64 v[2:3], 9, v[0:1]
	s_sub_i32 s0, s38, s1
	v_lshl_add_u64 v[4:5], s[2:3], 0, v[2:3]
	s_lshl_b32 s60, s52, 7
	v_and_b32_e32 v41, 7, v68
	v_lshl_add_u64 v[2:3], s[10:11], 0, v[2:3]
	s_mul_i32 s1, s18, 0x420
	s_mul_i32 s18, s52, 0x108
	v_lshl_add_u64 v[4:5], v[4:5], 0, s[60:61]
	v_lshlrev_b32_e32 v34, 4, v41
	v_mov_b32_e32 v35, v36
	v_lshl_add_u64 v[2:3], v[2:3], 0, s[60:61]
	s_add_i32 s1, s1, s18
	v_and_b32_e32 v69, 15, v68
	v_lshl_add_u64 v[4:5], v[4:5], 0, v[34:35]
	v_lshl_add_u64 v[2:3], v[2:3], 0, v[34:35]
	s_sub_i32 s1, s1, s19
	v_ashrrev_i32_e32 v55, 6, v68
	global_load_dwordx4 v[24:27], v[4:5], off
	global_load_dwordx4 v[20:23], v[2:3], off
	v_lshlrev_b32_e32 v2, 6, v69
	s_add_i32 s18, s51, s1
	v_lshl_or_b32 v2, v55, 10, v2
	s_ashr_i32 s19, s18, 31
	v_bfe_u32 v70, v68, 4, 2
	v_ashrrev_i32_e32 v3, 31, v2
	s_lshl_b64 s[38:39], s[18:19], 14
	s_addk_i32 s18, 0x84
	s_add_i32 s0, s37, s0
	v_lshl_add_u64 v[2:3], v[2:3], 1, s[20:21]
	v_lshlrev_b32_e32 v38, 4, v70
	v_mov_b32_e32 v39, v36
	s_ashr_i32 s19, s18, 31
	v_lshl_add_u64 v[2:3], v[2:3], 0, v[38:39]
	s_lshl_b64 s[18:19], s[18:19], 14
	v_lshlrev_b64 v[0:1], 10, v[0:1]
	s_ashr_i32 s1, s0, 31
	v_lshl_add_u64 v[4:5], v[2:3], 0, s[38:39]
	v_lshl_add_u64 v[2:3], v[2:3], 0, s[18:19]
	v_lshl_add_u64 v[0:1], s[14:15], 0, v[0:1]
	s_lshl_b32 s60, s52, 8
	s_lshl_b64 s[18:19], s[0:1], 10
	v_lshl_add_u64 v[0:1], v[0:1], 0, s[60:61]
	v_lshlrev_b32_e32 v42, 5, v41
	v_mov_b32_e32 v43, v36
	s_add_u32 s18, s13, s18
	v_lshl_add_u64 v[32:33], v[0:1], 0, v[42:43]
	s_addc_u32 s19, s24, s19
	v_mov_b32_e32 v35, v203
	global_load_dwordx4 v[16:19], v[4:5], off
	global_load_dwordx4 v[28:31], v[4:5], off offset:64
	global_load_dwordx4 v[12:15], v[2:3], off
	global_load_dwordx4 v[8:11], v[2:3], off offset:64
	s_nop 0
	global_load_dwordx4 v[0:3], v[32:33], off offset:16
	global_load_dwordx4 v[4:7], v[32:33], off
	s_add_u32 s18, s18, s60
	s_addc_u32 s19, s19, 0
	v_and_b32_e32 v39, 63, v35
	v_lshlrev_b32_e32 v48, 10, v39
	v_mov_b32_e32 v49, v36
	v_lshl_add_u32 v54, v39, 1, 0
	v_ashrrev_i32_e32 v39, 3, v35
	v_lshl_add_u64 v[52:53], s[18:19], 0, v[48:49]
	v_and_b32_e32 v48, -8, v39
	v_ashrrev_i32_e32 v49, 31, v48
	v_lshl_add_u64 v[50:51], v[48:49], 1, v[52:53]
	v_mad_u64_u32 v[56:57], s[18:19], v48, s76, v[54:55]
	global_load_dwordx4 v[48:51], v[50:51], off
	v_add_u32_e32 v35, 0x200, v35
	v_ashrrev_i32_e32 v35, 3, v35
	s_lshl_b64 s[0:1], s[0:1], 7
	s_add_u32 s42, s25, s0
	v_add_u32_e32 v42, 0, v42
	s_addc_u32 s43, s26, s1
	v_and_b32_e32 v120, -8, v35
	v_ashrrev_i32_e32 v121, 31, v120
	v_lshl_add_u64 v[120:121], v[120:121], 1, v[52:53]
	global_load_dwordx4 v[116:119], v[120:121], off
	v_ashrrev_i32_e32 v124, 3, v203
	v_ashrrev_i32_e32 v125, 31, v124
	v_lshlrev_b64 v[126:127], 7, v[124:125]
	v_lshl_add_u64 v[126:127], s[42:43], 0, v[126:127]
	v_lshlrev_b32_e32 v128, 3, v203
	v_and_b32_e32 v128, 56, v128
	v_mov_b32_e32 v129, v36
	v_lshl_add_u64 v[126:127], v[126:127], 0, v[128:129]
	global_load_dwordx2 v[130:131], v[126:127], off
	global_load_dwordx2 v[132:133], v[126:127], off offset:64
	v_sub_u32_e32 v34, v42, v34
	v_add_u32_e32 v66, 0, v38
	s_add_u32 s48, s44, s60
	s_addc_u32 s49, s45, 0
	s_add_u32 s53, s46, s60
	s_addc_u32 s54, s47, 0
	s_waitcnt vmcnt(0)
	ds_write_b16 v56, v48 offset:46336
	ds_write_b16_d16_hi v56, v48 offset:46480
	ds_write_b16 v56, v49 offset:46624
	ds_write_b16_d16_hi v56, v49 offset:46768
	ds_write_b16 v56, v50 offset:46912
	ds_write_b16_d16_hi v56, v50 offset:47056
	ds_write_b16 v56, v51 offset:47200
	ds_write_b16_d16_hi v56, v51 offset:47344
	v_and_b32_e32 v48, -8, v35
	v_ashrrev_i32_e32 v49, 31, v48
	v_mad_u64_u32 v[52:53], s[18:19], v48, s76, v[54:55]
	s_add_u32 s18, s48, s16
	s_addc_u32 s19, s49, s17
	s_waitcnt vmcnt(0)
	ds_write_b16 v52, v116 offset:46336
	ds_write_b16_d16_hi v52, v116 offset:46480
	ds_write_b16 v52, v117 offset:46624
	ds_write_b16_d16_hi v52, v117 offset:46768
	ds_write_b16 v52, v118 offset:46912
	ds_write_b16_d16_hi v52, v118 offset:47056
	ds_write_b16 v52, v119 offset:47200
	ds_write_b16_d16_hi v52, v119 offset:47344
	v_mad_u64_u32 v[48:49], s[0:1], v37, s56, v[42:43]
	v_mov_b32_e32 v49, v203
	v_mad_u64_u32 v[42:43], s[0:1], v37, s76, v[34:35]
	v_ashrrev_i32_e32 v50, 3, v49
	v_bfi_b32 v35, -16, v37, v68
	v_ashrrev_i32_e32 v51, 31, v50
	v_and_b32_e32 v34, -16, v37
	v_mad_u64_u32 v[38:39], s[0:1], v35, s76, v[66:67]
	v_lshlrev_b64 v[52:53], 7, v[50:51]
	v_lshlrev_b32_e32 v51, 3, v49
	v_lshlrev_b32_e32 v43, 5, v55
	v_lshl_or_b32 v39, v70, 2, v34
	v_lshl_or_b32 v34, v55, 4, v69
	v_lshl_add_u64 v[52:53], s[42:43], 0, v[52:53]
	v_and_b32_e32 v54, 56, v51
	v_mov_b32_e32 v55, v36
	v_lshl_add_u64 v[52:53], v[52:53], 0, v[54:55]
	v_lshlrev_b32_e32 v50, 6, v50
	v_add3_u32 v54, 0, v50, v54
	v_lshlrev_b32_e32 v64, 2, v49
	v_mad_u64_u32 v[34:35], s[0:1], v34, s76, v[66:67]
	s_add_u32 s0, s53, s30
	s_addc_u32 s1, s54, s31
	v_ashrrev_i32_e32 v49, 6, v49
	v_lshl_add_u32 v72, v49, 9, 0
	v_mul_u32_u24_e32 v35, 0x48, v69
	v_lshl_add_u32 v35, v35, 1, v66
	s_waitcnt vmcnt(0)
	ds_write_b64 v54, v[130:131] offset:64768
	v_and_b32_e32 v50, 0xfc, v64
	v_mov_b32_e32 v51, v36
	v_lshl_add_u64 v[52:53], s[18:19], 0, v[50:51]
	v_add_co_u32_e32 v54, vcc, s69, v52
	global_load_dword v51, v50, s[18:19]
	global_load_dword v65, v50, s[18:19] offset:1024
	global_load_dword v67, v50, s[18:19] offset:2048
	global_load_dword v71, v50, s[18:19] offset:3072
	v_addc_co_u32_e32 v55, vcc, 0, v53, vcc
	v_add_co_u32_e32 v56, vcc, s67, v52
	s_nop 1
	v_addc_co_u32_e32 v57, vcc, 0, v53, vcc
	v_add_co_u32_e32 v52, vcc, s66, v52
	global_load_dword v76, v[56:57], off offset:-4096
	global_load_dword v77, v[54:55], off offset:1024
	global_load_dword v78, v[54:55], off offset:2048
	global_load_dword v79, v[54:55], off offset:3072
	global_load_dword v80, v[56:57], off
	global_load_dword v81, v[56:57], off offset:1024
	global_load_dword v82, v[56:57], off offset:2048
	global_load_dword v83, v[56:57], off offset:3072
	v_addc_co_u32_e32 v53, vcc, 0, v53, vcc
	global_load_dword v84, v[52:53], off
	global_load_dword v85, v[52:53], off offset:1024
	global_load_dword v86, v[52:53], off offset:2048
	global_load_dword v87, v[52:53], off offset:3072
	global_load_dword v88, v50, s[0:1]
	s_waitcnt lgkmcnt(0)
	s_barrier
; __device__ __forceinline__ void gla_decay(unsigned char* lds, const float* glow_t0, const float* Wg  , const float* bg  , int dir) {
;     ...
;     float loc[8];
; #pragma unroll
;     for (int k = 0; k < 8; ++k) { const float* gl = GLs + (seg * 8 + k) * 16; float a = bias;
; #pragma unroll
;         for (int r = 0; r < 16; ++r) a += gl[r] * w[r];
;         loc[k] = (fminf(a, 0.f) - __logf(1.f + __expf(-fabsf(a)))) * (1.f / 16.f); }
	ds_read_b128 v[52:55], v72 offset:65216
	v_add_u32_e32 v50, 0, v50
	s_waitcnt vmcnt(0) lgkmcnt(0)
	v_fma_f32 v56, v51, v52, v88
	v_fmac_f32_e32 v56, v65, v53
	v_fmac_f32_e32 v56, v67, v54
	v_fmac_f32_e32 v56, v71, v55
	ds_read_b128 v[52:55], v72 offset:65232
	s_waitcnt lgkmcnt(0)
	v_fmac_f32_e32 v56, v76, v52
	v_fmac_f32_e32 v56, v77, v53
	v_fmac_f32_e32 v56, v78, v54
	v_fmac_f32_e32 v56, v79, v55
	ds_read_b128 v[52:55], v72 offset:65248
	s_waitcnt lgkmcnt(0)
	v_fmac_f32_e32 v56, v80, v52
	v_fmac_f32_e32 v56, v81, v53
	v_fmac_f32_e32 v56, v82, v54
	v_fmac_f32_e32 v56, v83, v55
	ds_read_b128 v[52:55], v72 offset:65264
	s_waitcnt lgkmcnt(0)
	v_fmac_f32_e32 v56, v84, v52
	v_fmac_f32_e32 v56, v85, v53
	v_fmac_f32_e32 v56, v86, v54
	v_fmac_f32_e32 v56, v87, v55
	v_mul_f32_e64 v53, |v56|, s55
	v_exp_f32_e32 v53, v53
	v_min_f32_e32 v52, 0, v56
	v_add_f32_e32 v53, 1.0, v53
	v_cmp_gt_f32_e32 vcc, s33, v53
	s_nop 1
	v_cndmask_b32_e64 v54, 0, 32, vcc
	v_ldexp_f32 v53, v53, v54
	v_log_f32_e32 v53, v53
	s_nop 0
	v_mul_f32_e32 v54, 0x3f317217, v53
	v_fma_f32 v54, v53, s57, -v54
	v_fmac_f32_e32 v54, 0x3377d1cf, v53
	v_fmac_f32_e32 v54, 0x3f317217, v53
	v_cmp_lt_f32_e64 s[38:39], |v53|, s58
	s_nop 1
	v_cndmask_b32_e64 v53, v53, v54, s[38:39]
	v_cndmask_b32_e32 v54, 0, v229, vcc
	v_sub_f32_e32 v53, v53, v54
	v_sub_f32_e32 v89, v52, v53
	ds_read_b128 v[52:55], v72 offset:65152
	s_waitcnt lgkmcnt(0)
	v_fma_f32 v56, v51, v52, v88
	v_fmac_f32_e32 v56, v65, v53
	v_fmac_f32_e32 v56, v67, v54
	v_fmac_f32_e32 v56, v71, v55
	ds_read_b128 v[52:55], v72 offset:65168
	s_waitcnt lgkmcnt(0)
	v_fmac_f32_e32 v56, v76, v52
	v_fmac_f32_e32 v56, v77, v53
	v_fmac_f32_e32 v56, v78, v54
	v_fmac_f32_e32 v56, v79, v55
	ds_read_b128 v[52:55], v72 offset:65184
	s_waitcnt lgkmcnt(0)
	v_fmac_f32_e32 v56, v80, v52
	v_fmac_f32_e32 v56, v81, v53
	v_fmac_f32_e32 v56, v82, v54
	v_fmac_f32_e32 v56, v83, v55
	ds_read_b128 v[52:55], v72 offset:65200
	s_waitcnt lgkmcnt(0)
	v_fmac_f32_e32 v56, v84, v52
	v_fmac_f32_e32 v56, v85, v53
	v_fmac_f32_e32 v56, v86, v54
	v_fmac_f32_e32 v56, v87, v55
	v_mul_f32_e64 v53, |v56|, s55
	v_exp_f32_e32 v53, v53
	v_min_f32_e32 v52, 0, v56
	v_add_f32_e32 v53, 1.0, v53
	v_cmp_gt_f32_e32 vcc, s33, v53
	s_nop 1
	v_cndmask_b32_e64 v54, 0, 32, vcc
	v_ldexp_f32 v53, v53, v54
	v_log_f32_e32 v53, v53
	s_nop 0
	v_mul_f32_e32 v54, 0x3f317217, v53
	v_fma_f32 v54, v53, s57, -v54
	v_fmac_f32_e32 v54, 0x3377d1cf, v53
	v_fmac_f32_e32 v54, 0x3f317217, v53
	v_cmp_lt_f32_e64 s[38:39], |v53|, s58
	s_nop 1
	v_cndmask_b32_e64 v53, v53, v54, s[38:39]
	v_cndmask_b32_e32 v54, 0, v229, vcc
	v_sub_f32_e32 v53, v53, v54
	v_sub_f32_e32 v90, v52, v53
	ds_read_b128 v[52:55], v72 offset:65088
	s_waitcnt lgkmcnt(0)
	v_fma_f32 v56, v51, v52, v88
	v_fmac_f32_e32 v56, v65, v53
	v_fmac_f32_e32 v56, v67, v54
	v_fmac_f32_e32 v56, v71, v55
	ds_read_b128 v[52:55], v72 offset:65104
	s_waitcnt lgkmcnt(0)
	v_fmac_f32_e32 v56, v76, v52
	v_fmac_f32_e32 v56, v77, v53
	v_fmac_f32_e32 v56, v78, v54
	v_fmac_f32_e32 v56, v79, v55
	ds_read_b128 v[52:55], v72 offset:65120
	s_waitcnt lgkmcnt(0)
	v_fmac_f32_e32 v56, v80, v52
	v_fmac_f32_e32 v56, v81, v53
	v_fmac_f32_e32 v56, v82, v54
	v_fmac_f32_e32 v56, v83, v55
	ds_read_b128 v[52:55], v72 offset:65136
	s_waitcnt lgkmcnt(0)
	v_fmac_f32_e32 v56, v84, v52
	v_fmac_f32_e32 v56, v85, v53
	v_fmac_f32_e32 v56, v86, v54
	v_fmac_f32_e32 v56, v87, v55
	v_mul_f32_e64 v53, |v56|, s55
	v_exp_f32_e32 v53, v53
	v_min_f32_e32 v52, 0, v56
	v_add_f32_e32 v53, 1.0, v53
	v_cmp_gt_f32_e32 vcc, s33, v53
	s_nop 1
	v_cndmask_b32_e64 v54, 0, 32, vcc
	v_ldexp_f32 v53, v53, v54
	v_log_f32_e32 v53, v53
	s_nop 0
	v_mul_f32_e32 v54, 0x3f317217, v53
	v_fma_f32 v54, v53, s57, -v54
	v_fmac_f32_e32 v54, 0x3377d1cf, v53
	v_fmac_f32_e32 v54, 0x3f317217, v53
	v_cmp_lt_f32_e64 s[38:39], |v53|, s58
	s_nop 1
	v_cndmask_b32_e64 v53, v53, v54, s[38:39]
	v_cndmask_b32_e32 v54, 0, v229, vcc
	v_sub_f32_e32 v53, v53, v54
	v_sub_f32_e32 v91, v52, v53
	ds_read_b128 v[52:55], v72 offset:65024
	s_waitcnt lgkmcnt(0)
	v_fma_f32 v56, v51, v52, v88
	v_fmac_f32_e32 v56, v65, v53
	v_fmac_f32_e32 v56, v67, v54
	v_fmac_f32_e32 v56, v71, v55
	ds_read_b128 v[52:55], v72 offset:65040
	s_waitcnt lgkmcnt(0)
	v_fmac_f32_e32 v56, v76, v52
	v_fmac_f32_e32 v56, v77, v53
	v_fmac_f32_e32 v56, v78, v54
	v_fmac_f32_e32 v56, v79, v55
	ds_read_b128 v[52:55], v72 offset:65056
	s_waitcnt lgkmcnt(0)
	v_fmac_f32_e32 v56, v80, v52
	v_fmac_f32_e32 v56, v81, v53
	v_fmac_f32_e32 v56, v82, v54
	v_fmac_f32_e32 v56, v83, v55
	ds_read_b128 v[52:55], v72 offset:65072
	s_waitcnt lgkmcnt(0)
	v_fmac_f32_e32 v56, v84, v52
	v_fmac_f32_e32 v56, v85, v53
	v_fmac_f32_e32 v56, v86, v54
	v_fmac_f32_e32 v56, v87, v55
	v_mul_f32_e64 v53, |v56|, s55
	v_exp_f32_e32 v53, v53
	v_min_f32_e32 v52, 0, v56
	v_add_f32_e32 v53, 1.0, v53
	v_cmp_gt_f32_e32 vcc, s33, v53
	s_nop 1
	v_cndmask_b32_e64 v54, 0, 32, vcc
	v_ldexp_f32 v53, v53, v54
	v_log_f32_e32 v53, v53
	s_nop 0
	v_mul_f32_e32 v54, 0x3f317217, v53
	v_fma_f32 v54, v53, s57, -v54
	v_fmac_f32_e32 v54, 0x3377d1cf, v53
	v_fmac_f32_e32 v54, 0x3f317217, v53
	v_cmp_lt_f32_e64 s[38:39], |v53|, s58
	s_nop 1
	v_cndmask_b32_e64 v53, v53, v54, s[38:39]
	v_cndmask_b32_e32 v54, 0, v229, vcc
	v_sub_f32_e32 v53, v53, v54
	v_sub_f32_e32 v92, v52, v53
	ds_read_b128 v[52:55], v72 offset:64960
	s_waitcnt lgkmcnt(0)
	v_fma_f32 v56, v51, v52, v88
	v_fmac_f32_e32 v56, v65, v53
	v_fmac_f32_e32 v56, v67, v54
	v_fmac_f32_e32 v56, v71, v55
	ds_read_b128 v[52:55], v72 offset:64976
	s_waitcnt lgkmcnt(0)
	v_fmac_f32_e32 v56, v76, v52
	v_fmac_f32_e32 v56, v77, v53
	v_fmac_f32_e32 v56, v78, v54
	v_fmac_f32_e32 v56, v79, v55
	ds_read_b128 v[52:55], v72 offset:64992
	s_waitcnt lgkmcnt(0)
; __device__ __forceinline__ void gla_decay(unsigned char* lds, const float* glow_t0, const float* Wg  , const float* bg  , int dir) {
;     ...
;     float loc[8];
; #pragma unroll
;     for (int k = 0; k < 8; ++k) { const float* gl = GLs + (seg * 8 + k) * 16; float a = bias;
; #pragma unroll
;         for (int r = 0; r < 16; ++r) a += gl[r] * w[r];
;         loc[k] = (fminf(a, 0.f) - __logf(1.f + __expf(-fabsf(a)))) * (1.f / 16.f); }
;     float run = 0.f;
;     if (dir == 0) {
; #pragma unroll
;         for (int k = 0; k < 8; ++k) { run += loc[k]; loc[k] = run; }
;     } else {
; #pragma unroll
;         for (int k = 7; k >= 0; --k) { run += loc[k]; loc[k] = run; }
;     }
;     Tot[seg * 64 + d] = run;
;     __syncthreads();
	v_fmac_f32_e32 v56, v80, v52
	v_fmac_f32_e32 v56, v81, v53
	v_fmac_f32_e32 v56, v82, v54
	v_fmac_f32_e32 v56, v83, v55
	ds_read_b128 v[52:55], v72 offset:65008
	s_waitcnt lgkmcnt(0)
	v_fmac_f32_e32 v56, v84, v52
	v_fmac_f32_e32 v56, v85, v53
	v_fmac_f32_e32 v56, v86, v54
	v_fmac_f32_e32 v56, v87, v55
	v_mul_f32_e64 v53, |v56|, s55
	v_exp_f32_e32 v53, v53
	v_min_f32_e32 v52, 0, v56
	v_add_f32_e32 v53, 1.0, v53
	v_cmp_gt_f32_e32 vcc, s33, v53
	s_nop 1
	v_cndmask_b32_e64 v54, 0, 32, vcc
	v_ldexp_f32 v53, v53, v54
	v_log_f32_e32 v53, v53
	s_nop 0
	v_mul_f32_e32 v54, 0x3f317217, v53
	v_fma_f32 v54, v53, s57, -v54
	v_fmac_f32_e32 v54, 0x3377d1cf, v53
	v_fmac_f32_e32 v54, 0x3f317217, v53
	v_cmp_lt_f32_e64 s[38:39], |v53|, s58
	s_nop 1
	v_cndmask_b32_e64 v53, v53, v54, s[38:39]
	v_cndmask_b32_e32 v54, 0, v229, vcc
	v_sub_f32_e32 v53, v53, v54
	v_sub_f32_e32 v93, v52, v53
	ds_read_b128 v[52:55], v72 offset:64896
	s_waitcnt lgkmcnt(0)
	v_fma_f32 v56, v51, v52, v88
	v_fmac_f32_e32 v56, v65, v53
	v_fmac_f32_e32 v56, v67, v54
	v_fmac_f32_e32 v56, v71, v55
	ds_read_b128 v[52:55], v72 offset:64912
	s_waitcnt lgkmcnt(0)
	v_fmac_f32_e32 v56, v76, v52
	v_fmac_f32_e32 v56, v77, v53
	v_fmac_f32_e32 v56, v78, v54
	v_fmac_f32_e32 v56, v79, v55
	ds_read_b128 v[52:55], v72 offset:64928
	s_waitcnt lgkmcnt(0)
	v_fmac_f32_e32 v56, v80, v52
	v_fmac_f32_e32 v56, v81, v53
	v_fmac_f32_e32 v56, v82, v54
	v_fmac_f32_e32 v56, v83, v55
	ds_read_b128 v[52:55], v72 offset:64944
	s_waitcnt lgkmcnt(0)
	v_fmac_f32_e32 v56, v84, v52
	v_fmac_f32_e32 v56, v85, v53
	v_fmac_f32_e32 v56, v86, v54
	v_fmac_f32_e32 v56, v87, v55
	v_mul_f32_e64 v53, |v56|, s55
	v_exp_f32_e32 v53, v53
	v_min_f32_e32 v52, 0, v56
	v_add_f32_e32 v53, 1.0, v53
	v_cmp_gt_f32_e32 vcc, s33, v53
	s_nop 1
	v_cndmask_b32_e64 v54, 0, 32, vcc
	v_ldexp_f32 v53, v53, v54
	v_log_f32_e32 v53, v53
	s_nop 0
	v_mul_f32_e32 v54, 0x3f317217, v53
	v_fma_f32 v54, v53, s57, -v54
	v_fmac_f32_e32 v54, 0x3377d1cf, v53
	v_fmac_f32_e32 v54, 0x3f317217, v53
	v_cmp_lt_f32_e64 s[38:39], |v53|, s58
	s_nop 1
	v_cndmask_b32_e64 v53, v53, v54, s[38:39]
	v_cndmask_b32_e32 v54, 0, v229, vcc
	v_sub_f32_e32 v53, v53, v54
	v_sub_f32_e32 v94, v52, v53
	ds_read_b128 v[52:55], v72 offset:64832
	s_waitcnt lgkmcnt(0)
	v_fma_f32 v56, v51, v52, v88
	v_fmac_f32_e32 v56, v65, v53
	v_fmac_f32_e32 v56, v67, v54
	v_fmac_f32_e32 v56, v71, v55
	ds_read_b128 v[52:55], v72 offset:64848
	s_waitcnt lgkmcnt(0)
	v_fmac_f32_e32 v56, v76, v52
	v_fmac_f32_e32 v56, v77, v53
	v_fmac_f32_e32 v56, v78, v54
	v_fmac_f32_e32 v56, v79, v55
	ds_read_b128 v[52:55], v72 offset:64864
	s_waitcnt lgkmcnt(0)
	v_fmac_f32_e32 v56, v80, v52
	v_fmac_f32_e32 v56, v81, v53
	v_fmac_f32_e32 v56, v82, v54
	v_fmac_f32_e32 v56, v83, v55
	ds_read_b128 v[52:55], v72 offset:64880
	s_waitcnt lgkmcnt(0)
	v_fmac_f32_e32 v56, v84, v52
	v_fmac_f32_e32 v56, v85, v53
	v_fmac_f32_e32 v56, v86, v54
	v_fmac_f32_e32 v56, v87, v55
	v_mul_f32_e64 v53, |v56|, s55
	v_exp_f32_e32 v53, v53
	v_min_f32_e32 v52, 0, v56
	v_add_f32_e32 v53, 1.0, v53
	v_cmp_gt_f32_e32 vcc, s33, v53
	s_nop 1
	v_cndmask_b32_e64 v54, 0, 32, vcc
	v_ldexp_f32 v53, v53, v54
	v_log_f32_e32 v53, v53
	s_nop 0
	v_mul_f32_e32 v54, 0x3f317217, v53
	v_fma_f32 v54, v53, s57, -v54
	v_fmac_f32_e32 v54, 0x3377d1cf, v53
	v_fmac_f32_e32 v54, 0x3f317217, v53
	v_cmp_lt_f32_e64 s[38:39], |v53|, s58
	s_nop 1
	v_cndmask_b32_e64 v53, v53, v54, s[38:39]
	v_cndmask_b32_e32 v54, 0, v229, vcc
	v_sub_f32_e32 v53, v53, v54
	v_sub_f32_e32 v95, v52, v53
	ds_read_b128 v[52:55], v72 offset:64768
	ds_read_b128 v[56:59], v72 offset:64784
	ds_read_b128 v[60:63], v72 offset:64800
	ds_read_b128 v[72:75], v72 offset:64816
	s_waitcnt lgkmcnt(3)
	v_fmac_f32_e32 v88, v51, v52
	v_fmac_f32_e32 v88, v65, v53
	v_fmac_f32_e32 v88, v67, v54
	v_fmac_f32_e32 v88, v71, v55
	s_waitcnt lgkmcnt(2)
	v_fmac_f32_e32 v88, v76, v56
	v_fmac_f32_e32 v88, v77, v57
	v_fmac_f32_e32 v88, v78, v58
	v_fmac_f32_e32 v88, v79, v59
	s_waitcnt lgkmcnt(1)
	v_fmac_f32_e32 v88, v80, v60
	v_fmac_f32_e32 v88, v81, v61
	v_fmac_f32_e32 v88, v82, v62
	v_fmac_f32_e32 v88, v83, v63
	s_waitcnt lgkmcnt(0)
	v_fmac_f32_e32 v88, v84, v72
	v_fmac_f32_e32 v88, v85, v73
	v_fmac_f32_e32 v88, v86, v74
	v_fmac_f32_e32 v88, v87, v75
	v_mul_f32_e64 v52, |v88|, s55
	v_exp_f32_e32 v52, v52
	v_min_f32_e32 v51, 0, v88
	v_lshlrev_b32_e32 v62, 16, v27
	v_and_b32_e32 v63, 0xffff0000, v27
	v_add_f32_e32 v52, 1.0, v52
	v_cmp_gt_f32_e32 vcc, s33, v52
	v_and_or_b32 v71, v43, 32, v69
	s_nop 0
	v_cndmask_b32_e64 v53, 0, 32, vcc
	v_ldexp_f32 v52, v52, v53
	v_log_f32_e32 v52, v52
	s_nop 0
	v_mul_f32_e32 v53, 0x3f317217, v52
	v_fma_f32 v53, v52, s57, -v53
	v_fmac_f32_e32 v53, 0x3377d1cf, v52
	v_fmac_f32_e32 v53, 0x3f317217, v52
	v_cmp_lt_f32_e64 s[38:39], |v52|, s58
	s_nop 1
	v_cndmask_b32_e64 v52, v52, v53, s[38:39]
	v_cndmask_b32_e32 v53, 0, v229, vcc
	v_sub_f32_e32 v52, v52, v53
	v_sub_f32_e32 v51, v51, v52
	v_fma_f32 v51, v51, s62, 0
	v_fmamk_f32 v54, v95, 0x3d800000, v51
	v_fmamk_f32 v55, v94, 0x3d800000, v54
	v_fmamk_f32 v56, v93, 0x3d800000, v55
	v_fmamk_f32 v57, v92, 0x3d800000, v56
	v_fmamk_f32 v58, v91, 0x3d800000, v57
	v_fmamk_f32 v59, v90, 0x3d800000, v58
	v_fmamk_f32 v60, v89, 0x3d800000, v59
	v_add_u32_e32 v52, 0, v64
	ds_write_b32 v52, v60 offset:16640
	s_waitcnt lgkmcnt(0)
	s_barrier
; __device__ __forceinline__ unsigned f2bf(float f) { unsigned u = __float_as_uint(f); return (u + 0x7fffu + ((u >> 16) & 1u)) >> 16; }
; __device__ __forceinline__ u32x4 pack8(const float* v) { u32x4 w; w.x = pk2(v[0], v[1]); w.y = pk2(v[2], v[3]); w.z = pk2(v[4], v[5]); w.w = pk2(v[6], v[7]); return w; }
; __device__ __forceinline__ void unpack8(u32x4 w, float* v) { v[0] = bflo(w.x); v[1] = bfhi(w.x); v[2] = bflo(w.y); v[3] = bfhi(w.y); v[4] = bflo(w.z); v[5] = bfhi(w.z); v[6] = bflo(w.w); v[7] = bfhi(w.w); }
; __device__ __forceinline__ void gla_decay(unsigned char* lds, const float* glow_t0, const float* Wg  , const float* bg  , int dir) {
;     ...
;     float off = 0.f;
; #pragma unroll
;     for (int sg = 0; sg < 8; ++sg) { const float tv = Tot[sg * 64 + d]; if (dir == 0 ? (sg < seg) : (sg > seg)) off += tv; }
; #pragma unroll
;     for (int k = 0; k < 8; ++k) Bs[(seg * 8 + k) * 65 + d] = loc[k] + off;
;     __syncthreads();
; __device__ __forceinline__ void gla_out_item(unsigned char* lds, unsigned char* ws, const float* wgate, const float* bgate, const float* hnorm, int l, int item, bool dowrite = true) {
;     ...
;         { const int s = tid >> 3, dg = tid & 7;
;           float qv[8], kv[8];
;           unpack8(qraw, qv);
;           unpack8(kraw, kv);
; #pragma unroll
;           for (int e = 0; e < 8; ++e) { const float bv = Bs[s * 65 + dg * 8 + e]; qv[e] *= __expf(bv); kv[e] *= __expf(-bv); }
;           *(u32x4*)(QE + s * 72 + dg * 8) = pack8(qv); *(u32x4*)(KE + s * 72 + dg * 8) = pack8(kv); }
;         __syncthreads();
;         { const int rb = wid >> 1;
; #pragma unroll
;           for (int cc = 0; cc < 2; ++cc) { const int cb = (wid & 1) * 2 + cc; f32x4 a4 = (f32x4){0.f, 0.f, 0.f, 0.f};
; #pragma unroll
;               for (int kk = 0; kk < 2; ++kk) { const bf16x8 a = *(const bf16x8*)(QE + (rb * 16 + ql) * 72 + kk * 32 + g * 8); const bf16x8 bb = *(const bf16x8*)(KE + (cb * 16 + ql) * 72 + kk * 32 + g * 8);
;                   a4 = __builtin_amdgcn_mfma_f32_16x16x32_bf16(a, bb, a4, 0, 0, 0); }
; #pragma unroll
;               for (int j = 0; j < 4; ++j) { const int i = rb * 16 + g * 4 + j, ip = cb * 16 + ql; const bool keep = dir == 0 ? (ip <= i) : (ip >= i); ATT[i * 72 + ip] = (bf16_t)f2bf(keep ? a4[j] : 0.f); } } }
	ds_read2st64_b32 v[52:53], v50 offset0:65 offset1:66
	v_cmp_lt_i32_e32 vcc, 0, v49
	s_waitcnt lgkmcnt(0)
	v_add_f32_e32 v52, 0, v52
	v_cndmask_b32_e32 v52, 0, v52, vcc
	v_cmp_lt_i32_e32 vcc, 1, v49
	v_add_f32_e32 v53, v53, v52
	s_nop 0
	v_cndmask_b32_e32 v61, v52, v53, vcc
	ds_read2st64_b32 v[52:53], v50 offset0:67 offset1:68
	v_cmp_lt_i32_e32 vcc, 2, v49
	s_waitcnt lgkmcnt(0)
	v_add_f32_e32 v52, v52, v61
	v_cndmask_b32_e32 v52, v61, v52, vcc
	v_cmp_lt_i32_e32 vcc, 3, v49
	v_add_f32_e32 v53, v53, v52
	s_nop 0
	v_cndmask_b32_e32 v61, v52, v53, vcc
	ds_read2st64_b32 v[52:53], v50 offset0:69 offset1:70
	v_cmp_lt_i32_e32 vcc, 4, v49
	s_waitcnt lgkmcnt(0)
	v_add_f32_e32 v52, v52, v61
	v_cndmask_b32_e32 v52, v61, v52, vcc
	v_cmp_lt_i32_e32 vcc, 5, v49
	v_add_f32_e32 v53, v53, v52
	s_nop 0
	v_cndmask_b32_e32 v61, v52, v53, vcc
	ds_read2st64_b32 v[52:53], v50 offset0:71 offset1:72
	v_cmp_lt_i32_e32 vcc, 6, v49
	s_waitcnt lgkmcnt(0)
	v_add_f32_e32 v52, v52, v61
	v_cndmask_b32_e32 v52, v61, v52, vcc
	v_cmp_lt_i32_e32 vcc, 7, v49
	v_add_f32_e32 v53, v53, v52
	s_nop 0
	v_cndmask_b32_e32 v52, v52, v53, vcc
	v_add_f32_e32 v53, v51, v52
	v_mad_u64_u32 v[50:51], s[0:1], v49, s59, v[50:51]
	v_add_f32_e32 v49, v54, v52
	ds_write2_b32 v50, v53, v49 offset1:65
	v_add_f32_e32 v49, v55, v52
	v_add_f32_e32 v51, v56, v52
	ds_write2_b32 v50, v49, v51 offset0:130 offset1:195
	v_add_f32_e32 v49, v57, v52
	v_add_f32_e32 v51, v58, v52
	v_add_u32_e32 v50, 0x400, v50
	ds_write2_b32 v50, v49, v51 offset0:4 offset1:69
	v_add_f32_e32 v49, v59, v52
	v_add_f32_e32 v51, v60, v52
	ds_write2_b32 v50, v49, v51 offset0:134 offset1:199
	s_waitcnt lgkmcnt(0)
	s_barrier
	ds_read2_b32 v[52:53], v48 offset1:1
	v_lshlrev_b32_e32 v50, 16, v24
	v_and_b32_e32 v51, 0xffff0000, v24
	v_cmp_gt_i32_e32 vcc, v71, v39
	s_waitcnt lgkmcnt(0)
	v_mul_f32_e32 v49, 0x3fb8aa3b, v52
	v_exp_f32_e32 v54, v49
	v_mul_f32_e32 v49, 0xbfb8aa3b, v52
	v_mul_f32_e32 v24, 0xbfb8aa3b, v53
	v_exp_f32_e32 v56, v49
	v_exp_f32_e32 v57, v24
	v_mul_f32_e32 v49, 0x3fb8aa3b, v53
	v_lshlrev_b32_e32 v52, 16, v20
	v_and_b32_e32 v53, 0xffff0000, v20
	v_pk_mul_f32 v[74:75], v[56:57], v[52:53]
	ds_read2_b32 v[56:57], v48 offset0:2 offset1:3
	v_exp_f32_e32 v55, v49
	s_waitcnt lgkmcnt(0)
	v_mul_f32_e32 v20, 0x3fb8aa3b, v56
	v_exp_f32_e32 v58, v20
	v_mul_f32_e32 v20, 0xbfb8aa3b, v56
	v_exp_f32_e32 v24, v20
	v_mul_f32_e32 v20, 0x3fb8aa3b, v57
	v_exp_f32_e32 v59, v20
	v_mul_f32_e32 v20, 0xbfb8aa3b, v57
	v_pk_mul_f32 v[72:73], v[54:55], v[50:51]
	v_lshlrev_b32_e32 v54, 16, v25
	v_and_b32_e32 v55, 0xffff0000, v25
	v_exp_f32_e32 v25, v20
	v_lshlrev_b32_e32 v56, 16, v21
	v_and_b32_e32 v57, 0xffff0000, v21
	ds_read2_b32 v[20:21], v48 offset0:4 offset1:5
	v_pk_mul_f32 v[76:77], v[58:59], v[54:55]
	v_lshlrev_b32_e32 v58, 16, v26
	v_and_b32_e32 v59, 0xffff0000, v26
	v_pk_mul_f32 v[24:25], v[24:25], v[56:57]
	s_waitcnt lgkmcnt(0)
	v_mul_f32_e32 v49, 0x3fb8aa3b, v20
	v_exp_f32_e32 v60, v49
	v_mul_f32_e32 v49, 0x3fb8aa3b, v21
	v_mul_f32_e32 v20, 0xbfb8aa3b, v20
	v_exp_f32_e32 v61, v49
	v_mul_f32_e32 v21, 0xbfb8aa3b, v21
	v_exp_f32_e32 v20, v20
	v_exp_f32_e32 v21, v21
	v_pk_mul_f32 v[78:79], v[60:61], v[58:59]
	v_lshlrev_b32_e32 v60, 16, v22
	v_and_b32_e32 v61, 0xffff0000, v22
	v_pk_mul_f32 v[80:81], v[20:21], v[60:61]
	ds_read2_b32 v[20:21], v48 offset0:6 offset1:7
	v_mad_u32_u24 v49, v71, s76, v66
	v_or_b32_e32 v66, 1, v39
	v_cmp_le_i32_e64 s[38:39], v71, v66
	s_waitcnt lgkmcnt(0)
	v_mul_f32_e32 v22, 0x3fb8aa3b, v20
	v_exp_f32_e32 v64, v22
	v_mul_f32_e32 v22, 0x3fb8aa3b, v21
	v_mul_f32_e32 v20, 0xbfb8aa3b, v20
	v_exp_f32_e32 v65, v22
	v_mul_f32_e32 v21, 0xbfb8aa3b, v21
	v_exp_f32_e32 v20, v20
	v_exp_f32_e32 v21, v21
	v_pk_mul_f32 v[26:27], v[64:65], v[62:63]
	v_lshlrev_b32_e32 v64, 16, v23
	v_and_b32_e32 v65, 0xffff0000, v23
	v_pk_mul_f32 v[82:83], v[20:21], v[64:65]
	v_cvt_pk_bf16_f32 v20, v72, v73
	v_cvt_pk_bf16_f32 v21, v76, v77
	v_cvt_pk_bf16_f32 v22, v78, v79
	v_cvt_pk_bf16_f32 v23, v26, v27
	ds_write_b128 v42, v[20:23] offset:18688
	v_cvt_pk_bf16_f32 v20, v74, v75
	v_cvt_pk_bf16_f32 v21, v24, v25
	v_cvt_pk_bf16_f32 v22, v80, v81
	v_cvt_pk_bf16_f32 v23, v82, v83
	ds_write_b128 v42, v[20:23] offset:27904
	s_waitcnt lgkmcnt(0)
	s_barrier
	ds_read_b128 v[20:23], v38 offset:18688
	ds_read_b128 v[24:27], v49 offset:27904
	s_waitcnt lgkmcnt(0)
	v_mfma_f32_16x16x32_bf16 v[20:23], v[20:23], v[24:27], 0
	ds_read_b128 v[24:27], v38 offset:18752
	ds_read_b128 v[72:75], v49 offset:27968
	s_waitcnt lgkmcnt(0)
	v_mfma_f32_16x16x32_bf16 v[20:23], v[24:27], v[72:75], v[20:23]
	v_lshlrev_b32_e32 v24, 1, v71
	v_or_b32_e32 v72, 2, v39
	v_or_b32_e32 v73, 3, v39
	s_nop 4
	v_cndmask_b32_e64 v20, v20, 0, vcc
	v_bfe_u32 v25, v20, 16, 1
	v_add3_u32 v20, v20, v25, s86
	v_mul_lo_u32 v25, v39, s76
	v_add3_u32 v43, 0, v24, v25
	ds_write_b16_d16_hi v43, v20 offset:37120
	v_cndmask_b32_e64 v20, 0, v21, s[38:39]
	v_bfe_u32 v21, v20, 16, 1
	v_add3_u32 v20, v20, v21, s86
	v_cmp_le_i32_e64 s[38:39], v71, v72
	ds_write_b16_d16_hi v43, v20 offset:37264
	v_or_b32_e32 v74, 16, v71
	v_cndmask_b32_e64 v20, 0, v22, s[38:39]
	v_bfe_u32 v21, v20, 16, 1
	v_add3_u32 v20, v20, v21, s86
	v_cmp_le_i32_e64 s[38:39], v71, v73
	ds_write_b16_d16_hi v43, v20 offset:37408
	v_cmp_le_i32_e64 s[40:41], v74, v66
	v_cndmask_b32_e64 v20, 0, v23, s[38:39]
	v_bfe_u32 v21, v20, 16, 1
	v_add3_u32 v20, v20, v21, s86
	ds_write_b16_d16_hi v43, v20 offset:37552
	ds_read_b128 v[20:23], v38 offset:18688
	ds_read_b128 v[24:27], v49 offset:30208
	s_waitcnt lgkmcnt(0)
	v_mfma_f32_16x16x32_bf16 v[20:23], v[20:23], v[24:27], 0
	ds_read_b128 v[24:27], v38 offset:18752
	ds_read_b128 v[76:79], v49 offset:30272
	v_cmp_gt_i32_e64 s[38:39], v74, v39
	v_mov_b32_e32 v75, v203
	s_waitcnt lgkmcnt(0)
	v_mfma_f32_16x16x32_bf16 v[20:23], v[24:27], v[76:79], v[20:23]
	s_nop 7
	v_cndmask_b32_e64 v20, v20, 0, s[38:39]
	v_bfe_u32 v24, v20, 16, 1
	v_add3_u32 v20, v20, v24, s86
	ds_write_b16_d16_hi v43, v20 offset:37152
	v_cndmask_b32_e64 v20, 0, v21, s[40:41]
	v_bfe_u32 v21, v20, 16, 1
	v_add3_u32 v20, v20, v21, s86
	v_cmp_le_i32_e64 s[40:41], v74, v72
	ds_write_b16_d16_hi v43, v20 offset:37296
	s_nop 0
	v_cndmask_b32_e64 v20, 0, v22, s[40:41]
	v_bfe_u32 v21, v20, 16, 1
	v_add3_u32 v20, v20, v21, s86
	v_cmp_le_i32_e64 s[40:41], v74, v73
	ds_write_b16_d16_hi v43, v20 offset:37440
	s_nop 0
	v_cndmask_b32_e64 v20, 0, v23, s[40:41]
	v_bfe_u32 v21, v20, 16, 1
	v_add3_u32 v20, v20, v21, s86
	ds_write_b16_d16_hi v43, v20 offset:37584
	s_waitcnt lgkmcnt(0)
	s_barrier
; __device__ __forceinline__ void gla_decay(unsigned char* lds, const float* glow_t0, const float* Wg  , const float* bg  , int dir) {
;     float* Bs = (float*)(lds + GL_BS); float* Tot = (float*)(lds + GL_TOT); float* GLs = (float*)(lds + GL_O);
;     int tid_ = threadIdx.x; asm volatile("" : "+v"(tid_)); const int tid = tid_;
;     { const int s = tid >> 3, q = tid & 7;
;       const float* gp = glow_t0 + (size_t)s * 32 + dir * 16 + q * 2;
;       GLs[s * 16 + q * 2] = gp[0]; GLs[s * 16 + q * 2 + 1] = gp[1]; }
;     const int d = tid & 63, seg = tid >> 6;
;     float w[16];
; #pragma unroll
;     for (int r = 0; r < 16; ++r) w[r] = Wg[r * 256 + d];
;     const float bias = bg[d];
;     __syncthreads();
;     float loc[8];
; #pragma unroll
;     for (int k = 0; k < 8; ++k) { const float* gl = GLs + (seg * 8 + k) * 16; float a = bias;
; #pragma unroll
;         for (int r = 0; r < 16; ++r) a += gl[r] * w[r];
;         loc[k] = (fminf(a, 0.f) - __logf(1.f + __expf(-fabsf(a)))) * (1.f / 16.f); }
; __device__ __forceinline__ void gla_out_item(unsigned char* lds, unsigned char* ws, const float* wgate, const float* bgate, const float* hnorm, int l, int item, bool dowrite = true) {
;     ...
;         { const int sidx = ((b * 4 + h) * 2 + dir) * 132 + c;
;           const bf16_t* st = (const bf16_t*)(ws + O_ST) + (size_t)sidx * 8192;
; #pragma unroll
;           for (int kk = 0; kk < 2; ++kk) {
;               const bf16x8 bv = *(const bf16x8*)(Vt + (wid * 16 + ql) * 72 + kk * 32 + g * 8);
;               const bf16x8 bs = dir == 0 ? sfr[0][kk] : sfr[1][kk];
; #pragma unroll
;               for (int rb = 0; rb < 4; ++rb) {
;                   const bf16x8 a1 = *(const bf16x8*)(ATT + (rb * 16 + ql) * 72 + kk * 32 + g * 8);
;                   const bf16x8 a2 = *(const bf16x8*)(QE + (rb * 16 + ql) * 72 + kk * 32 + g * 8);
;                   oacc[rb] = __builtin_amdgcn_mfma_f32_16x16x32_bf16(a1, bv, oacc[rb], 0, 0, 0);
;                   oacc[rb] = __builtin_amdgcn_mfma_f32_16x16x32_bf16(a2, bs, oacc[rb], 0, 0, 0);
;               } } }
	ds_read_b128 v[20:23], v34 offset:46336
	ds_read_b128 v[24:27], v35 offset:37120
	ds_read_b128 v[76:79], v35 offset:18688
	s_waitcnt lgkmcnt(1)
	v_mfma_f32_16x16x32_bf16 v[24:27], v[24:27], v[20:23], 0
	s_add_u32 s40, s48, s28
	s_addc_u32 s41, s49, s29
	s_add_u32 s48, s53, s34
	s_waitcnt lgkmcnt(0)
	v_mfma_f32_16x16x32_bf16 v[24:27], v[76:79], v[16:19], v[24:27]
	ds_read_b128 v[76:79], v35 offset:39424
	ds_read_b128 v[80:83], v35 offset:20992
	s_addc_u32 s49, s54, s35
	s_waitcnt lgkmcnt(1)
	v_mfma_f32_16x16x32_bf16 v[76:79], v[76:79], v[20:23], 0
	s_waitcnt lgkmcnt(0)
	v_mfma_f32_16x16x32_bf16 v[76:79], v[80:83], v[16:19], v[76:79]
	ds_read_b128 v[80:83], v35 offset:41728
	ds_read_b128 v[84:87], v35 offset:23296
	s_waitcnt lgkmcnt(1)
	v_mfma_f32_16x16x32_bf16 v[80:83], v[80:83], v[20:23], 0
	s_waitcnt lgkmcnt(0)
	v_mfma_f32_16x16x32_bf16 v[80:83], v[84:87], v[16:19], v[80:83]
	ds_read_b128 v[84:87], v35 offset:44032
	ds_read_b128 v[88:91], v35 offset:25600
	s_waitcnt lgkmcnt(1)
	v_mfma_f32_16x16x32_bf16 v[20:23], v[84:87], v[20:23], 0
	s_waitcnt lgkmcnt(0)
	v_mfma_f32_16x16x32_bf16 v[84:87], v[88:91], v[16:19], v[20:23]
	ds_read_b128 v[88:91], v34 offset:46400
	ds_read_b128 v[16:19], v35 offset:37184
	s_nop 3
	ds_read_b128 v[20:23], v35 offset:18752
	s_waitcnt lgkmcnt(1)
	v_mfma_f32_16x16x32_bf16 v[16:19], v[16:19], v[88:91], v[24:27]
	s_waitcnt lgkmcnt(0)
	v_mfma_f32_16x16x32_bf16 v[16:19], v[20:23], v[28:31], v[16:19]
	ds_read_b128 v[20:23], v35 offset:39488
	ds_read_b128 v[24:27], v35 offset:21056
	s_waitcnt lgkmcnt(1)
	v_mfma_f32_16x16x32_bf16 v[20:23], v[20:23], v[88:91], v[76:79]
	s_waitcnt lgkmcnt(0)
	v_mfma_f32_16x16x32_bf16 v[20:23], v[24:27], v[28:31], v[20:23]
	ds_read_b128 v[24:27], v35 offset:41792
	ds_read_b128 v[76:79], v35 offset:23360
	s_waitcnt lgkmcnt(1)
	v_mfma_f32_16x16x32_bf16 v[24:27], v[24:27], v[88:91], v[80:83]
	s_waitcnt lgkmcnt(0)
	v_mfma_f32_16x16x32_bf16 v[24:27], v[76:79], v[28:31], v[24:27]
	ds_read_b128 v[76:79], v35 offset:44096
	ds_read_b128 v[80:83], v35 offset:25664
	s_waitcnt lgkmcnt(0)
	s_barrier
	v_mfma_f32_16x16x32_bf16 v[76:79], v[76:79], v[88:91], v[84:87]
	s_nop 0
	v_ashrrev_i32_e32 v66, 3, v75
	v_ashrrev_i32_e32 v67, 31, v66
	v_mfma_f32_16x16x32_bf16 v[28:31], v[80:83], v[28:31], v[76:79]
	v_lshlrev_b32_e32 v92, 2, v75
	s_nop 2
	v_lshlrev_b64 v[76:77], 7, v[66:67]
	v_lshlrev_b32_e32 v67, 3, v75
	v_lshl_add_u64 v[76:77], s[42:43], 0, v[76:77]
	v_and_b32_e32 v78, 56, v67
	v_mov_b32_e32 v79, v36
	v_lshl_add_u64 v[76:77], v[76:77], 0, v[78:79]
	v_lshlrev_b32_e32 v66, 6, v66
	v_add3_u32 v78, 0, v66, v78
	v_ashrrev_i32_e32 v75, 6, v75
	v_lshl_add_u32 v88, v75, 9, 0
	s_waitcnt vmcnt(0)
	ds_write_b64 v78, v[132:133] offset:64768
	v_and_b32_e32 v66, 0xfc, v92
	v_mov_b32_e32 v67, v36
	v_lshl_add_u64 v[76:77], s[40:41], 0, v[66:67]
	global_load_dword v67, v66, s[40:41]
	global_load_dword v93, v66, s[40:41] offset:1024
	global_load_dword v94, v66, s[40:41] offset:2048
	global_load_dword v95, v66, s[40:41] offset:3072
	v_add_co_u32_e64 v78, s[40:41], s69, v76
	s_nop 1
	v_addc_co_u32_e64 v79, s[40:41], 0, v77, s[40:41]
	v_add_co_u32_e64 v80, s[40:41], s67, v76
	s_nop 1
	v_addc_co_u32_e64 v81, s[40:41], 0, v77, s[40:41]
	v_add_co_u32_e64 v76, s[40:41], s66, v76
	global_load_dword v96, v[80:81], off offset:-4096
	global_load_dword v97, v[78:79], off offset:1024
	global_load_dword v98, v[78:79], off offset:2048
	global_load_dword v99, v[78:79], off offset:3072
	global_load_dword v100, v[80:81], off
	global_load_dword v101, v[80:81], off offset:1024
	global_load_dword v102, v[80:81], off offset:2048
	global_load_dword v103, v[80:81], off offset:3072
	v_addc_co_u32_e64 v77, s[40:41], 0, v77, s[40:41]
	global_load_dword v104, v[76:77], off
	global_load_dword v105, v[76:77], off offset:1024
	global_load_dword v106, v[76:77], off offset:2048
	global_load_dword v107, v[76:77], off offset:3072
	global_load_dword v108, v66, s[48:49]
	s_waitcnt lgkmcnt(0)
	s_barrier
	ds_read_b128 v[76:79], v88 offset:65216
	v_add_u32_e32 v66, 0, v66
	s_waitcnt vmcnt(0) lgkmcnt(0)
	v_fma_f32 v80, v67, v76, v108
	v_fmac_f32_e32 v80, v93, v77
	v_fmac_f32_e32 v80, v94, v78
	v_fmac_f32_e32 v80, v95, v79
	ds_read_b128 v[76:79], v88 offset:65232
	s_waitcnt lgkmcnt(0)
	v_fmac_f32_e32 v80, v96, v76
	v_fmac_f32_e32 v80, v97, v77
	v_fmac_f32_e32 v80, v98, v78
	v_fmac_f32_e32 v80, v99, v79
	ds_read_b128 v[76:79], v88 offset:65248
	s_waitcnt lgkmcnt(0)
	v_fmac_f32_e32 v80, v100, v76
	v_fmac_f32_e32 v80, v101, v77
	v_fmac_f32_e32 v80, v102, v78
	v_fmac_f32_e32 v80, v103, v79
	ds_read_b128 v[76:79], v88 offset:65264
	s_waitcnt lgkmcnt(0)
	v_fmac_f32_e32 v80, v104, v76
	v_fmac_f32_e32 v80, v105, v77
	v_fmac_f32_e32 v80, v106, v78
	v_fmac_f32_e32 v80, v107, v79
	v_mul_f32_e64 v77, |v80|, s55
	v_exp_f32_e32 v77, v77
	v_min_f32_e32 v76, 0, v80
	v_add_f32_e32 v77, 1.0, v77
	v_cmp_gt_f32_e64 s[40:41], s33, v77
	s_nop 1
	v_cndmask_b32_e64 v78, 0, 32, s[40:41]
	v_ldexp_f32 v77, v77, v78
	v_log_f32_e32 v77, v77
	s_nop 0
	v_mul_f32_e32 v78, 0x3f317217, v77
	v_fma_f32 v78, v77, s57, -v78
	v_fmac_f32_e32 v78, 0x3377d1cf, v77
	v_fmac_f32_e32 v78, 0x3f317217, v77
	v_cmp_lt_f32_e64 s[42:43], |v77|, s58
	s_nop 1
	v_cndmask_b32_e64 v77, v77, v78, s[42:43]
	v_cndmask_b32_e64 v78, 0, v229, s[40:41]
	v_sub_f32_e32 v77, v77, v78
	v_sub_f32_e32 v109, v76, v77
	ds_read_b128 v[76:79], v88 offset:65152
	s_waitcnt lgkmcnt(0)
	v_fma_f32 v80, v67, v76, v108
	v_fmac_f32_e32 v80, v93, v77
	v_fmac_f32_e32 v80, v94, v78
	v_fmac_f32_e32 v80, v95, v79
	ds_read_b128 v[76:79], v88 offset:65168
	s_waitcnt lgkmcnt(0)
; __device__ __forceinline__ void gla_decay(unsigned char* lds, const float* glow_t0, const float* Wg  , const float* bg  , int dir) {
;     ...
;     float loc[8];
; #pragma unroll
;     for (int k = 0; k < 8; ++k) { const float* gl = GLs + (seg * 8 + k) * 16; float a = bias;
; #pragma unroll
;         for (int r = 0; r < 16; ++r) a += gl[r] * w[r];
;         loc[k] = (fminf(a, 0.f) - __logf(1.f + __expf(-fabsf(a)))) * (1.f / 16.f); }
	v_fmac_f32_e32 v80, v96, v76
	v_fmac_f32_e32 v80, v97, v77
	v_fmac_f32_e32 v80, v98, v78
	v_fmac_f32_e32 v80, v99, v79
	ds_read_b128 v[76:79], v88 offset:65184
	s_waitcnt lgkmcnt(0)
	v_fmac_f32_e32 v80, v100, v76
	v_fmac_f32_e32 v80, v101, v77
	v_fmac_f32_e32 v80, v102, v78
	v_fmac_f32_e32 v80, v103, v79
	ds_read_b128 v[76:79], v88 offset:65200
	s_waitcnt lgkmcnt(0)
	v_fmac_f32_e32 v80, v104, v76
	v_fmac_f32_e32 v80, v105, v77
	v_fmac_f32_e32 v80, v106, v78
	v_fmac_f32_e32 v80, v107, v79
	v_mul_f32_e64 v77, |v80|, s55
	v_exp_f32_e32 v77, v77
	v_min_f32_e32 v76, 0, v80
	v_add_f32_e32 v77, 1.0, v77
	v_cmp_gt_f32_e64 s[40:41], s33, v77
	s_nop 1
	v_cndmask_b32_e64 v78, 0, 32, s[40:41]
	v_ldexp_f32 v77, v77, v78
	v_log_f32_e32 v77, v77
	s_nop 0
	v_mul_f32_e32 v78, 0x3f317217, v77
	v_fma_f32 v78, v77, s57, -v78
	v_fmac_f32_e32 v78, 0x3377d1cf, v77
	v_fmac_f32_e32 v78, 0x3f317217, v77
	v_cmp_lt_f32_e64 s[42:43], |v77|, s58
	s_nop 1
	v_cndmask_b32_e64 v77, v77, v78, s[42:43]
	v_cndmask_b32_e64 v78, 0, v229, s[40:41]
	v_sub_f32_e32 v77, v77, v78
	v_sub_f32_e32 v110, v76, v77
	ds_read_b128 v[76:79], v88 offset:65088
	s_waitcnt lgkmcnt(0)
	v_fma_f32 v80, v67, v76, v108
	v_fmac_f32_e32 v80, v93, v77
	v_fmac_f32_e32 v80, v94, v78
	v_fmac_f32_e32 v80, v95, v79
	ds_read_b128 v[76:79], v88 offset:65104
	s_waitcnt lgkmcnt(0)
	v_fmac_f32_e32 v80, v96, v76
	v_fmac_f32_e32 v80, v97, v77
	v_fmac_f32_e32 v80, v98, v78
	v_fmac_f32_e32 v80, v99, v79
	ds_read_b128 v[76:79], v88 offset:65120
	s_waitcnt lgkmcnt(0)
	v_fmac_f32_e32 v80, v100, v76
	v_fmac_f32_e32 v80, v101, v77
	v_fmac_f32_e32 v80, v102, v78
	v_fmac_f32_e32 v80, v103, v79
	ds_read_b128 v[76:79], v88 offset:65136
	s_waitcnt lgkmcnt(0)
	v_fmac_f32_e32 v80, v104, v76
	v_fmac_f32_e32 v80, v105, v77
	v_fmac_f32_e32 v80, v106, v78
	v_fmac_f32_e32 v80, v107, v79
	v_mul_f32_e64 v77, |v80|, s55
	v_exp_f32_e32 v77, v77
	v_min_f32_e32 v76, 0, v80
	v_add_f32_e32 v77, 1.0, v77
	v_cmp_gt_f32_e64 s[40:41], s33, v77
	s_nop 1
	v_cndmask_b32_e64 v78, 0, 32, s[40:41]
	v_ldexp_f32 v77, v77, v78
	v_log_f32_e32 v77, v77
	s_nop 0
	v_mul_f32_e32 v78, 0x3f317217, v77
	v_fma_f32 v78, v77, s57, -v78
	v_fmac_f32_e32 v78, 0x3377d1cf, v77
	v_fmac_f32_e32 v78, 0x3f317217, v77
	v_cmp_lt_f32_e64 s[42:43], |v77|, s58
	s_nop 1
	v_cndmask_b32_e64 v77, v77, v78, s[42:43]
	v_cndmask_b32_e64 v78, 0, v229, s[40:41]
	v_sub_f32_e32 v77, v77, v78
	v_sub_f32_e32 v111, v76, v77
	ds_read_b128 v[76:79], v88 offset:65024
	s_waitcnt lgkmcnt(0)
	v_fma_f32 v80, v67, v76, v108
	v_fmac_f32_e32 v80, v93, v77
	v_fmac_f32_e32 v80, v94, v78
	v_fmac_f32_e32 v80, v95, v79
	ds_read_b128 v[76:79], v88 offset:65040
	s_waitcnt lgkmcnt(0)
	v_fmac_f32_e32 v80, v96, v76
	v_fmac_f32_e32 v80, v97, v77
	v_fmac_f32_e32 v80, v98, v78
	v_fmac_f32_e32 v80, v99, v79
	ds_read_b128 v[76:79], v88 offset:65056
	s_waitcnt lgkmcnt(0)
	v_fmac_f32_e32 v80, v100, v76
	v_fmac_f32_e32 v80, v101, v77
	v_fmac_f32_e32 v80, v102, v78
	v_fmac_f32_e32 v80, v103, v79
	ds_read_b128 v[76:79], v88 offset:65072
	s_waitcnt lgkmcnt(0)
	v_fmac_f32_e32 v80, v104, v76
	v_fmac_f32_e32 v80, v105, v77
	v_fmac_f32_e32 v80, v106, v78
	v_fmac_f32_e32 v80, v107, v79
	v_mul_f32_e64 v77, |v80|, s55
	v_exp_f32_e32 v77, v77
	v_min_f32_e32 v76, 0, v80
	v_add_f32_e32 v77, 1.0, v77
	v_cmp_gt_f32_e64 s[40:41], s33, v77
	s_nop 1
	v_cndmask_b32_e64 v78, 0, 32, s[40:41]
	v_ldexp_f32 v77, v77, v78
	v_log_f32_e32 v77, v77
	s_nop 0
	v_mul_f32_e32 v78, 0x3f317217, v77
	v_fma_f32 v78, v77, s57, -v78
	v_fmac_f32_e32 v78, 0x3377d1cf, v77
	v_fmac_f32_e32 v78, 0x3f317217, v77
	v_cmp_lt_f32_e64 s[42:43], |v77|, s58
	s_nop 1
	v_cndmask_b32_e64 v77, v77, v78, s[42:43]
	v_cndmask_b32_e64 v78, 0, v229, s[40:41]
	v_sub_f32_e32 v77, v77, v78
	v_sub_f32_e32 v112, v76, v77
	ds_read_b128 v[76:79], v88 offset:64960
	s_waitcnt lgkmcnt(0)
	v_fma_f32 v80, v67, v76, v108
	v_fmac_f32_e32 v80, v93, v77
	v_fmac_f32_e32 v80, v94, v78
	v_fmac_f32_e32 v80, v95, v79
	ds_read_b128 v[76:79], v88 offset:64976
	s_waitcnt lgkmcnt(0)
	v_fmac_f32_e32 v80, v96, v76
	v_fmac_f32_e32 v80, v97, v77
	v_fmac_f32_e32 v80, v98, v78
	v_fmac_f32_e32 v80, v99, v79
	ds_read_b128 v[76:79], v88 offset:64992
	s_waitcnt lgkmcnt(0)
	v_fmac_f32_e32 v80, v100, v76
	v_fmac_f32_e32 v80, v101, v77
	v_fmac_f32_e32 v80, v102, v78
	v_fmac_f32_e32 v80, v103, v79
	ds_read_b128 v[76:79], v88 offset:65008
	s_waitcnt lgkmcnt(0)
	v_fmac_f32_e32 v80, v104, v76
	v_fmac_f32_e32 v80, v105, v77
	v_fmac_f32_e32 v80, v106, v78
	v_fmac_f32_e32 v80, v107, v79
	v_mul_f32_e64 v77, |v80|, s55
	v_exp_f32_e32 v77, v77
	v_min_f32_e32 v76, 0, v80
	v_add_f32_e32 v77, 1.0, v77
	v_cmp_gt_f32_e64 s[40:41], s33, v77
	s_nop 1
	v_cndmask_b32_e64 v78, 0, 32, s[40:41]
	v_ldexp_f32 v77, v77, v78
	v_log_f32_e32 v77, v77
	s_nop 0
	v_mul_f32_e32 v78, 0x3f317217, v77
	v_fma_f32 v78, v77, s57, -v78
	v_fmac_f32_e32 v78, 0x3377d1cf, v77
	v_fmac_f32_e32 v78, 0x3f317217, v77
	v_cmp_lt_f32_e64 s[42:43], |v77|, s58
	s_nop 1
	v_cndmask_b32_e64 v77, v77, v78, s[42:43]
	v_cndmask_b32_e64 v78, 0, v229, s[40:41]
	v_sub_f32_e32 v77, v77, v78
	v_sub_f32_e32 v113, v76, v77
	ds_read_b128 v[76:79], v88 offset:64896
	s_waitcnt lgkmcnt(0)
	v_fma_f32 v80, v67, v76, v108
	v_fmac_f32_e32 v80, v93, v77
	v_fmac_f32_e32 v80, v94, v78
	v_fmac_f32_e32 v80, v95, v79
	ds_read_b128 v[76:79], v88 offset:64912
	s_waitcnt lgkmcnt(0)
	v_fmac_f32_e32 v80, v96, v76
	v_fmac_f32_e32 v80, v97, v77
	v_fmac_f32_e32 v80, v98, v78
	v_fmac_f32_e32 v80, v99, v79
	ds_read_b128 v[76:79], v88 offset:64928
	s_waitcnt lgkmcnt(0)
	v_fmac_f32_e32 v80, v100, v76
	v_fmac_f32_e32 v80, v101, v77
	v_fmac_f32_e32 v80, v102, v78
	v_fmac_f32_e32 v80, v103, v79
	ds_read_b128 v[76:79], v88 offset:64944
	s_waitcnt lgkmcnt(0)
; __device__ __forceinline__ void gla_decay(unsigned char* lds, const float* glow_t0, const float* Wg  , const float* bg  , int dir) {
;     ...
;     float loc[8];
; #pragma unroll
;     for (int k = 0; k < 8; ++k) { const float* gl = GLs + (seg * 8 + k) * 16; float a = bias;
; #pragma unroll
;         for (int r = 0; r < 16; ++r) a += gl[r] * w[r];
;         loc[k] = (fminf(a, 0.f) - __logf(1.f + __expf(-fabsf(a)))) * (1.f / 16.f); }
;     float run = 0.f;
;     if (dir == 0) {
; #pragma unroll
;         for (int k = 0; k < 8; ++k) { run += loc[k]; loc[k] = run; }
;     } else {
; #pragma unroll
;         for (int k = 7; k >= 0; --k) { run += loc[k]; loc[k] = run; }
;     }
;     Tot[seg * 64 + d] = run;
;     __syncthreads();
;     float off = 0.f;
; #pragma unroll
;     for (int sg = 0; sg < 8; ++sg) { const float tv = Tot[sg * 64 + d]; if (dir == 0 ? (sg < seg) : (sg > seg)) off += tv; }
; #pragma unroll
;     for (int k = 0; k < 8; ++k) Bs[(seg * 8 + k) * 65 + d] = loc[k] + off;
;     __syncthreads();
	v_fmac_f32_e32 v80, v104, v76
	v_fmac_f32_e32 v80, v105, v77
	v_fmac_f32_e32 v80, v106, v78
	v_fmac_f32_e32 v80, v107, v79
	v_mul_f32_e64 v77, |v80|, s55
	v_exp_f32_e32 v77, v77
	v_min_f32_e32 v76, 0, v80
	v_add_f32_e32 v77, 1.0, v77
	v_cmp_gt_f32_e64 s[40:41], s33, v77
	s_nop 1
	v_cndmask_b32_e64 v78, 0, 32, s[40:41]
	v_ldexp_f32 v77, v77, v78
	v_log_f32_e32 v77, v77
	s_nop 0
	v_mul_f32_e32 v78, 0x3f317217, v77
	v_fma_f32 v78, v77, s57, -v78
	v_fmac_f32_e32 v78, 0x3377d1cf, v77
	v_fmac_f32_e32 v78, 0x3f317217, v77
	v_cmp_lt_f32_e64 s[42:43], |v77|, s58
	s_nop 1
	v_cndmask_b32_e64 v77, v77, v78, s[42:43]
	v_cndmask_b32_e64 v78, 0, v229, s[40:41]
	v_sub_f32_e32 v77, v77, v78
	v_sub_f32_e32 v114, v76, v77
	ds_read_b128 v[76:79], v88 offset:64832
	s_waitcnt lgkmcnt(0)
	v_fma_f32 v80, v67, v76, v108
	v_fmac_f32_e32 v80, v93, v77
	v_fmac_f32_e32 v80, v94, v78
	v_fmac_f32_e32 v80, v95, v79
	ds_read_b128 v[76:79], v88 offset:64848
	s_waitcnt lgkmcnt(0)
	v_fmac_f32_e32 v80, v96, v76
	v_fmac_f32_e32 v80, v97, v77
	v_fmac_f32_e32 v80, v98, v78
	v_fmac_f32_e32 v80, v99, v79
	ds_read_b128 v[76:79], v88 offset:64864
	s_waitcnt lgkmcnt(0)
	v_fmac_f32_e32 v80, v100, v76
	v_fmac_f32_e32 v80, v101, v77
	v_fmac_f32_e32 v80, v102, v78
	v_fmac_f32_e32 v80, v103, v79
	ds_read_b128 v[76:79], v88 offset:64880
	s_waitcnt lgkmcnt(0)
	v_fmac_f32_e32 v80, v104, v76
	v_fmac_f32_e32 v80, v105, v77
	v_fmac_f32_e32 v80, v106, v78
	v_fmac_f32_e32 v80, v107, v79
	v_mul_f32_e64 v77, |v80|, s55
	v_exp_f32_e32 v77, v77
	v_min_f32_e32 v76, 0, v80
	v_add_f32_e32 v77, 1.0, v77
	v_cmp_gt_f32_e64 s[40:41], s33, v77
	s_nop 1
	v_cndmask_b32_e64 v78, 0, 32, s[40:41]
	v_ldexp_f32 v77, v77, v78
	v_log_f32_e32 v77, v77
	s_nop 0
	v_mul_f32_e32 v78, 0x3f317217, v77
	v_fma_f32 v78, v77, s57, -v78
	v_fmac_f32_e32 v78, 0x3377d1cf, v77
	v_fmac_f32_e32 v78, 0x3f317217, v77
	v_cmp_lt_f32_e64 s[42:43], |v77|, s58
	s_nop 1
	v_cndmask_b32_e64 v77, v77, v78, s[42:43]
	v_cndmask_b32_e64 v78, 0, v229, s[40:41]
	v_sub_f32_e32 v77, v77, v78
	v_sub_f32_e32 v115, v76, v77
	ds_read_b128 v[76:79], v88 offset:64768
	ds_read_b128 v[80:83], v88 offset:64784
	ds_read_b128 v[84:87], v88 offset:64800
	ds_read_b128 v[88:91], v88 offset:64816
	s_waitcnt lgkmcnt(3)
	v_fmac_f32_e32 v108, v67, v76
	v_fmac_f32_e32 v108, v93, v77
	v_fmac_f32_e32 v108, v94, v78
	v_fmac_f32_e32 v108, v95, v79
	s_waitcnt lgkmcnt(2)
	v_fmac_f32_e32 v108, v96, v80
	v_fmac_f32_e32 v108, v97, v81
	v_fmac_f32_e32 v108, v98, v82
	v_fmac_f32_e32 v108, v99, v83
	s_waitcnt lgkmcnt(1)
	v_fmac_f32_e32 v108, v100, v84
	v_fmac_f32_e32 v108, v101, v85
	v_fmac_f32_e32 v108, v102, v86
	v_fmac_f32_e32 v108, v103, v87
	s_waitcnt lgkmcnt(0)
	v_fmac_f32_e32 v108, v104, v88
	v_fmac_f32_e32 v108, v105, v89
	v_fmac_f32_e32 v108, v106, v90
	v_fmac_f32_e32 v108, v107, v91
	v_mul_f32_e64 v76, |v108|, s55
	v_exp_f32_e32 v76, v76
	v_fma_f32 v78, v109, s62, 0
	v_fmamk_f32 v79, v110, 0x3d800000, v78
	v_fmamk_f32 v80, v111, 0x3d800000, v79
	v_add_f32_e32 v76, 1.0, v76
	v_cmp_gt_f32_e64 s[40:41], s33, v76
	v_fmamk_f32 v81, v112, 0x3d800000, v80
	v_fmamk_f32 v82, v113, 0x3d800000, v81
	v_cndmask_b32_e64 v77, 0, 32, s[40:41]
	v_ldexp_f32 v76, v76, v77
	v_log_f32_e32 v76, v76
	v_min_f32_e32 v67, 0, v108
	v_fmamk_f32 v83, v114, 0x3d800000, v82
	v_fmamk_f32 v84, v115, 0x3d800000, v83
	v_mul_f32_e32 v77, 0x3f317217, v76
	v_fma_f32 v77, v76, s57, -v77
	v_fmac_f32_e32 v77, 0x3377d1cf, v76
	v_fmac_f32_e32 v77, 0x3f317217, v76
	v_cmp_lt_f32_e64 s[42:43], |v76|, s58
	s_nop 1
	v_cndmask_b32_e64 v76, v76, v77, s[42:43]
	v_cndmask_b32_e64 v77, 0, v229, s[40:41]
	v_sub_f32_e32 v76, v76, v77
	v_sub_f32_e32 v67, v67, v76
	v_fmamk_f32 v67, v67, 0x3d800000, v84
	v_add_u32_e32 v76, 0, v92
	ds_write_b32 v76, v67 offset:16640
	s_waitcnt lgkmcnt(0)
	s_barrier
	ds_read2st64_b32 v[76:77], v66 offset0:65 offset1:66
	v_cmp_gt_i32_e64 s[40:41], 0, v75
	s_waitcnt lgkmcnt(0)
	v_add_f32_e32 v76, 0, v76
	v_cndmask_b32_e64 v76, 0, v76, s[40:41]
	v_cmp_gt_i32_e64 s[40:41], 1, v75
	v_add_f32_e32 v76, v77, v76
	s_nop 0
	v_cndmask_b32_e64 v85, 0, v76, s[40:41]
	ds_read2st64_b32 v[76:77], v66 offset0:67 offset1:68
	v_cmp_gt_i32_e64 s[40:41], 2, v75
	s_waitcnt lgkmcnt(0)
	v_add_f32_e32 v76, v76, v85
	v_cndmask_b32_e64 v76, 0, v76, s[40:41]
	v_cmp_gt_i32_e64 s[40:41], 3, v75
	v_add_f32_e32 v76, v77, v76
	s_nop 0
	v_cndmask_b32_e64 v85, 0, v76, s[40:41]
	ds_read2st64_b32 v[76:77], v66 offset0:69 offset1:70
	v_cmp_gt_i32_e64 s[40:41], 4, v75
	s_waitcnt lgkmcnt(0)
	v_add_f32_e32 v76, v76, v85
	v_cndmask_b32_e64 v76, 0, v76, s[40:41]
	v_cmp_gt_i32_e64 s[40:41], 5, v75
	v_add_f32_e32 v76, v77, v76
	s_nop 0
	v_cndmask_b32_e64 v85, 0, v76, s[40:41]
	ds_read2st64_b32 v[76:77], v66 offset0:71 offset1:72
	v_cmp_gt_i32_e64 s[40:41], 6, v75
	s_waitcnt lgkmcnt(0)
	v_add_f32_e32 v76, v76, v85
	v_cndmask_b32_e64 v76, 0, v76, s[40:41]
	v_cmp_gt_i32_e64 s[40:41], 7, v75
	v_add_f32_e32 v76, v77, v76
	s_nop 0
	v_cndmask_b32_e64 v76, 0, v76, s[40:41]
	v_add_f32_e32 v77, v67, v76
	v_mad_u64_u32 v[66:67], s[0:1], v75, s59, v[66:67]
	v_add_f32_e32 v67, v84, v76
	ds_write2_b32 v66, v77, v67 offset1:65
	v_add_f32_e32 v67, v83, v76
	v_add_f32_e32 v75, v82, v76
	ds_write2_b32 v66, v67, v75 offset0:130 offset1:195
	v_add_f32_e32 v67, v81, v76
	v_add_f32_e32 v75, v80, v76
	v_add_u32_e32 v66, 0x400, v66
	ds_write2_b32 v66, v67, v75 offset0:4 offset1:69
	v_add_f32_e32 v67, v79, v76
	v_add_f32_e32 v75, v78, v76
	ds_write2_b32 v66, v67, v75 offset0:134 offset1:199
	s_waitcnt lgkmcnt(0)
	s_barrier
; __device__ __forceinline__ void gla_out_item(unsigned char* lds, unsigned char* ws, const float* wgate, const float* bgate, const float* hnorm, int l, int item, bool dowrite = true) {
;     ...
;     for (int dir = 0; dir < 2; ++dir) {
;         gla_decay(lds, (const float*)(ws + O_GLOW) + (size_t)t0 * 32, wgate + (size_t)((l * 2 + dir) * 16) * 256 + h * 64, bgate + (l * 2 + dir) * 256 + h * 64, dir);
;         { const int s = tid >> 3, dg = tid & 7;
;           float qv[8], kv[8];
;           unpack8(qraw, qv);
;           unpack8(kraw, kv);
; #pragma unroll
;           for (int e = 0; e < 8; ++e) { const float bv = Bs[s * 65 + dg * 8 + e]; qv[e] *= __expf(bv); kv[e] *= __expf(-bv); }
;           *(u32x4*)(QE + s * 72 + dg * 8) = pack8(qv); *(u32x4*)(KE + s * 72 + dg * 8) = pack8(kv); }
;         __syncthreads();
;         { const int rb = wid >> 1;
; #pragma unroll
;           for (int cc = 0; cc < 2; ++cc) { const int cb = (wid & 1) * 2 + cc; f32x4 a4 = (f32x4){0.f, 0.f, 0.f, 0.f};
; #pragma unroll
;               for (int kk = 0; kk < 2; ++kk) { const bf16x8 a = *(const bf16x8*)(QE + (rb * 16 + ql) * 72 + kk * 32 + g * 8); const bf16x8 bb = *(const bf16x8*)(KE + (cb * 16 + ql) * 72 + kk * 32 + g * 8);
;                   a4 = __builtin_amdgcn_mfma_f32_16x16x32_bf16(a, bb, a4, 0, 0, 0); }
; #pragma unroll
;               for (int j = 0; j < 4; ++j) { const int i = rb * 16 + g * 4 + j, ip = cb * 16 + ql; const bool keep = dir == 0 ? (ip <= i) : (ip >= i); ATT[i * 72 + ip] = (bf16_t)f2bf(keep ? a4[j] : 0.f); } } }
;         __syncthreads();
;         { const int sidx = ((b * 4 + h) * 2 + dir) * 132 + c;
;           const bf16_t* st = (const bf16_t*)(ws + O_ST) + (size_t)sidx * 8192;
; #pragma unroll
;           for (int kk = 0; kk < 2; ++kk) {
;               const bf16x8 bv = *(const bf16x8*)(Vt + (wid * 16 + ql) * 72 + kk * 32 + g * 8);
;               const bf16x8 bs = dir == 0 ? sfr[0][kk] : sfr[1][kk];
; #pragma unroll
;               for (int rb = 0; rb < 4; ++rb) {
;                   const bf16x8 a1 = *(const bf16x8*)(ATT + (rb * 16 + ql) * 72 + kk * 32 + g * 8);
;                   const bf16x8 a2 = *(const bf16x8*)(QE + (rb * 16 + ql) * 72 + kk * 32 + g * 8);
;                   oacc[rb] = __builtin_amdgcn_mfma_f32_16x16x32_bf16(a1, bv, oacc[rb], 0, 0, 0);
;                   oacc[rb] = __builtin_amdgcn_mfma_f32_16x16x32_bf16(a2, bs, oacc[rb], 0, 0, 0);
	ds_read2_b32 v[66:67], v48 offset1:1
	v_cmp_ge_i32_e64 s[40:41], v71, v39
	s_movk_i32 s0, 0x210
	s_waitcnt lgkmcnt(0)
	v_mul_f32_e32 v75, 0x3fb8aa3b, v66
	v_exp_f32_e32 v76, v75
	v_mul_f32_e32 v66, 0xbfb8aa3b, v66
	v_mul_f32_e32 v75, 0x3fb8aa3b, v67
	v_mul_f32_e32 v67, 0xbfb8aa3b, v67
	v_exp_f32_e32 v66, v66
	v_exp_f32_e32 v67, v67
	v_exp_f32_e32 v77, v75
	v_pk_mul_f32 v[66:67], v[66:67], v[52:53]
	ds_read2_b32 v[52:53], v48 offset0:2 offset1:3
	v_pk_mul_f32 v[50:51], v[76:77], v[50:51]
	s_waitcnt lgkmcnt(0)
	v_mul_f32_e32 v75, 0x3fb8aa3b, v52
	v_exp_f32_e32 v76, v75
	v_mul_f32_e32 v52, 0xbfb8aa3b, v52
	v_mul_f32_e32 v75, 0x3fb8aa3b, v53
	v_mul_f32_e32 v53, 0xbfb8aa3b, v53
	v_exp_f32_e32 v52, v52
	v_exp_f32_e32 v53, v53
	v_exp_f32_e32 v77, v75
	v_cvt_pk_bf16_f32 v50, v50, v51
	v_pk_mul_f32 v[56:57], v[52:53], v[56:57]
	ds_read2_b32 v[52:53], v48 offset0:4 offset1:5
	v_pk_mul_f32 v[54:55], v[76:77], v[54:55]
	s_waitcnt lgkmcnt(0)
	v_mul_f32_e32 v75, 0x3fb8aa3b, v52
	v_exp_f32_e32 v76, v75
	v_mul_f32_e32 v52, 0xbfb8aa3b, v52
	v_mul_f32_e32 v75, 0x3fb8aa3b, v53
	v_mul_f32_e32 v53, 0xbfb8aa3b, v53
	v_exp_f32_e32 v52, v52
	v_exp_f32_e32 v53, v53
	v_exp_f32_e32 v77, v75
	v_cvt_pk_bf16_f32 v51, v54, v55
	v_pk_mul_f32 v[60:61], v[52:53], v[60:61]
	ds_read2_b32 v[52:53], v48 offset0:6 offset1:7
	v_pk_mul_f32 v[58:59], v[76:77], v[58:59]
	s_waitcnt lgkmcnt(0)
	v_mul_f32_e32 v48, 0x3fb8aa3b, v52
	v_exp_f32_e32 v76, v48
	v_mul_f32_e32 v48, 0xbfb8aa3b, v52
	v_exp_f32_e32 v52, v48
	v_mul_f32_e32 v48, 0x3fb8aa3b, v53
	v_exp_f32_e32 v77, v48
	v_mul_f32_e32 v48, 0xbfb8aa3b, v53
	v_exp_f32_e32 v53, v48
	v_pk_mul_f32 v[62:63], v[76:77], v[62:63]
	v_pk_mul_f32 v[64:65], v[52:53], v[64:65]
	v_cvt_pk_bf16_f32 v52, v58, v59
	v_cvt_pk_bf16_f32 v53, v62, v63
	ds_write_b128 v42, v[50:53] offset:18688
	v_cvt_pk_bf16_f32 v50, v66, v67
	v_cvt_pk_bf16_f32 v51, v56, v57
	v_cvt_pk_bf16_f32 v52, v60, v61
	v_cvt_pk_bf16_f32 v53, v64, v65
	ds_write_b128 v42, v[50:53] offset:27904
	s_waitcnt lgkmcnt(0)
	s_barrier
	ds_read_b128 v[50:53], v38 offset:18688
	ds_read_b128 v[54:57], v49 offset:27904
	s_waitcnt lgkmcnt(0)
	v_mfma_f32_16x16x32_bf16 v[50:53], v[50:53], v[54:57], 0
	ds_read_b128 v[54:57], v38 offset:18752
	ds_read_b128 v[58:61], v49 offset:27968
	v_and_b32_e32 v67, 0xffff0000, v0
	s_waitcnt lgkmcnt(0)
	v_mfma_f32_16x16x32_bf16 v[50:53], v[54:57], v[58:61], v[50:53]
	s_nop 7
	v_cndmask_b32_e64 v42, 0, v50, s[40:41]
	v_bfe_u32 v48, v42, 16, 1
	v_add3_u32 v42, v42, v48, s86
	ds_write_b16_d16_hi v43, v42 offset:37120
	v_cndmask_b32_e32 v42, 0, v51, vcc
	v_bfe_u32 v48, v42, 16, 1
	v_add3_u32 v42, v42, v48, s86
	v_cmp_ge_i32_e32 vcc, v71, v72
	ds_write_b16_d16_hi v43, v42 offset:37264
	s_nop 0
	v_cndmask_b32_e32 v42, 0, v52, vcc
	v_bfe_u32 v48, v42, 16, 1
	v_add3_u32 v42, v42, v48, s86
	v_cmp_ge_i32_e32 vcc, v71, v73
	ds_write_b16_d16_hi v43, v42 offset:37408
	s_nop 0
	v_cndmask_b32_e32 v42, 0, v53, vcc
	v_bfe_u32 v48, v42, 16, 1
	v_add3_u32 v42, v42, v48, s86
	ds_write_b16_d16_hi v43, v42 offset:37552
	ds_read_b128 v[50:53], v38 offset:18688
	ds_read_b128 v[54:57], v49 offset:30208
	s_waitcnt lgkmcnt(0)
	v_mfma_f32_16x16x32_bf16 v[50:53], v[50:53], v[54:57], 0
	ds_read_b128 v[54:57], v38 offset:18752
	ds_read_b128 v[58:61], v49 offset:30272
	v_cmp_ge_i32_e32 vcc, v74, v39
	v_lshlrev_b32_e32 v42, 16, v6
	s_waitcnt lgkmcnt(0)
	v_mfma_f32_16x16x32_bf16 v[48:51], v[54:57], v[58:61], v[50:53]
	s_nop 7
	v_cndmask_b32_e32 v38, 0, v48, vcc
	v_bfe_u32 v39, v38, 16, 1
	v_add3_u32 v38, v38, v39, s86
	ds_write_b16_d16_hi v43, v38 offset:37152
	v_cndmask_b32_e64 v38, 0, v49, s[38:39]
	v_bfe_u32 v39, v38, 16, 1
	v_add3_u32 v38, v38, v39, s86
	v_cmp_ge_i32_e32 vcc, v74, v72
	ds_write_b16_d16_hi v43, v38 offset:37296
	s_nop 0
	v_cndmask_b32_e32 v38, 0, v50, vcc
	v_bfe_u32 v39, v38, 16, 1
	v_add3_u32 v38, v38, v39, s86
	v_cmp_ge_i32_e32 vcc, v74, v73
	ds_write_b16_d16_hi v43, v38 offset:37440
	s_nop 0
	v_cndmask_b32_e32 v38, 0, v51, vcc
	v_bfe_u32 v39, v38, 16, 1
	v_add3_u32 v38, v38, v39, s86
	ds_write_b16_d16_hi v43, v38 offset:37584
	s_waitcnt lgkmcnt(0)
	s_barrier
	ds_read_b128 v[48:51], v34 offset:46336
	ds_read_b128 v[52:55], v35 offset:37120
	ds_read_b128 v[56:59], v35 offset:18688
	s_waitcnt lgkmcnt(1)
	v_mfma_f32_16x16x32_bf16 v[16:19], v[52:55], v[48:51], v[16:19]
	v_and_b32_e32 v43, 0xffff0000, v6
	v_mul_f32_e32 v6, 0xbfb8aa3b, v42
	v_exp_f32_e32 v6, v6
	s_waitcnt lgkmcnt(0)
	v_mfma_f32_16x16x32_bf16 v[16:19], v[56:59], v[12:15], v[16:19]
	ds_read_b128 v[52:55], v35 offset:39424
	ds_read_b128 v[56:59], v35 offset:20992
	v_cmp_lt_i32_e32 vcc, v220, v219
	s_waitcnt lgkmcnt(1)
	v_mfma_f32_16x16x32_bf16 v[20:23], v[52:55], v[48:51], v[20:23]
	s_waitcnt lgkmcnt(0)
	v_mfma_f32_16x16x32_bf16 v[20:23], v[56:59], v[12:15], v[20:23]
	ds_read_b128 v[52:55], v35 offset:41728
	ds_read_b128 v[56:59], v35 offset:23296
	s_waitcnt lgkmcnt(1)
	v_mfma_f32_16x16x32_bf16 v[24:27], v[52:55], v[48:51], v[24:27]
	s_waitcnt lgkmcnt(0)
	v_mfma_f32_16x16x32_bf16 v[24:27], v[56:59], v[12:15], v[24:27]
	ds_read_b128 v[52:55], v35 offset:44032
	ds_read_b128 v[56:59], v35 offset:25600
	s_waitcnt lgkmcnt(1)
	v_mfma_f32_16x16x32_bf16 v[28:31], v[52:55], v[48:51], v[28:31]
	s_waitcnt lgkmcnt(0)
	v_mfma_f32_16x16x32_bf16 v[12:15], v[56:59], v[12:15], v[28:31]
	s_nop 5
	ds_read_b128 v[28:31], v34 offset:46400
	ds_read_b128 v[48:51], v35 offset:37184
	ds_read_b128 v[52:55], v35 offset:18752
	s_waitcnt lgkmcnt(1)
	v_mfma_f32_16x16x32_bf16 v[16:19], v[48:51], v[28:31], v[16:19]
	s_waitcnt lgkmcnt(0)
	v_mfma_f32_16x16x32_bf16 v[16:19], v[52:55], v[8:11], v[16:19]
	ds_read_b128 v[48:51], v35 offset:39488
	ds_read_b128 v[52:55], v35 offset:21056
	s_waitcnt lgkmcnt(1)
	v_mfma_f32_16x16x32_bf16 v[20:23], v[48:51], v[28:31], v[20:23]
	s_waitcnt lgkmcnt(0)
	v_mfma_f32_16x16x32_bf16 v[20:23], v[52:55], v[8:11], v[20:23]
	ds_read_b128 v[48:51], v35 offset:41792
	ds_read_b128 v[52:55], v35 offset:23360
	s_waitcnt lgkmcnt(1)
	v_mfma_f32_16x16x32_bf16 v[24:27], v[48:51], v[28:31], v[24:27]
	s_waitcnt lgkmcnt(0)
	v_mfma_f32_16x16x32_bf16 v[24:27], v[52:55], v[8:11], v[24:27]
	ds_read_b128 v[48:51], v35 offset:44096
	ds_read_b128 v[52:55], v35 offset:25664
	s_waitcnt lgkmcnt(0)
	s_barrier
; __device__ __forceinline__ void gla_out_item(unsigned char* lds, unsigned char* ws, const float* wgate, const float* bgate, const float* hnorm, int l, int item, bool dowrite = true) {
;     ...
;         __syncthreads();
;     }
;     float* Os = (float*)(lds + GL_O);
; #pragma unroll
;     for (int rb = 0; rb < 4; ++rb)
; #pragma unroll
;         for (int j = 0; j < 4; ++j) Os[(rb * 16 + g * 4 + j) * 132 + wid * 16 + ql] = oacc[rb][j];
;     __syncthreads();
	v_mfma_f32_16x16x32_bf16 v[12:15], v[48:51], v[28:31], v[12:15]
	v_lshlrev_b32_e32 v28, 6, v41
	v_and_b32_e32 v41, 0xffff0000, v7
	v_mfma_f32_16x16x32_bf16 v[8:11], v[52:55], v[8:11], v[12:15]
	v_cndmask_b32_e32 v29, v218, v220, vcc
	v_cmp_lt_i32_e32 vcc, v221, v219
	v_lshlrev_b32_e32 v29, 2, v29
	s_nop 1
	v_and_b32_e32 v12, 0xffffffc0, v68
	v_add_u32_e32 v12, 0, v12
	v_lshlrev_b32_e32 v13, 2, v69
	v_mul_u32_u24_e32 v14, 0x840, v70
	v_add3_u32 v12, v12, v13, v14
	v_add_u32_e32 v13, 0xfd00, v12
	v_add_u32_e32 v12, 0xfc00, v12
	ds_write2_b32 v12, v16, v17 offset0:64 offset1:196
	v_add_u32_e32 v12, 0x400, v13
	ds_write2_b32 v12, v18, v19 offset0:8 offset1:140
	v_add_u32_e32 v12, 0x2000, v13
	ds_write2_b32 v12, v20, v21 offset0:64 offset1:196
	v_add_u32_e32 v12, 0x2400, v13
	ds_write2_b32 v12, v22, v23 offset0:72 offset1:204
	v_add_u32_e32 v12, 0x4200, v13
	ds_write2_b32 v12, v24, v25 offset1:132
	v_add_u32_e32 v12, 0x4600, v13
	ds_write2_b32 v12, v26, v27 offset0:8 offset1:140
	v_add_u32_e32 v12, 0x6200, v13
	ds_write2_b32 v12, v8, v9 offset0:64 offset1:196
	v_add_u32_e32 v8, 0x6600, v13
	ds_write2_b32 v8, v10, v11 offset0:72 offset1:204
	v_mul_lo_u32 v8, v37, s0
	v_lshlrev_b32_e32 v37, 16, v7
	v_mul_f32_e32 v7, 0xbfb8aa3b, v43
	v_exp_f32_e32 v7, v7
	v_cndmask_b32_e32 v30, v218, v221, vcc
	v_cmp_lt_i32_e32 vcc, v222, v219
	s_lshl_b32 s0, s52, 9
	v_pk_add_f32 v[6:7], v[6:7], 1.0 op_sel_hi:[1,0]
	v_cndmask_b32_e32 v31, v218, v222, vcc
	s_add_u32 s0, s27, s0
	v_add3_u32 v8, 0, v8, v28
	s_addc_u32 s1, s36, 0
	v_rcp_f32_e32 v56, v7
	s_nop 0
	v_mul_f32_e32 v7, v43, v56
	s_waitcnt lgkmcnt(0)
	s_barrier
; __device__ __forceinline__ u32x4 pack8(const float* v) { u32x4 w; w.x = pk2(v[0], v[1]); w.y = pk2(v[2], v[3]); w.z = pk2(v[4], v[5]); w.w = pk2(v[6], v[7]); return w; }
; __device__ __forceinline__ void unpack8(u32x4 w, float* v) { v[0] = bflo(w.x); v[1] = bfhi(w.x); v[2] = bflo(w.y); v[3] = bfhi(w.y); v[4] = bflo(w.z); v[5] = bfhi(w.z); v[6] = bflo(w.w); v[7] = bfhi(w.w); }
; __device__ __forceinline__ float siluf_(float x) { return x / (1.f + __expf(-x)); }
; __device__ __forceinline__ void gla_out_item(unsigned char* lds, unsigned char* ws, const float* wgate, const float* bgate, const float* hnorm, int l, int item, bool dowrite = true) {
;     ...
;     { const int i = tid >> 3, eg = tid & 7;
;       float ov[16]; float ss = 0.f;
; #pragma unroll
;       for (int e = 0; e < 16; ++e) { ov[e] = Os[i * 132 + eg * 16 + e]; ss += ov[e] * ov[e]; }
;       ss += __shfl_xor(ss, 1); ss += __shfl_xor(ss, 2); ss += __shfl_xor(ss, 4);
;       const float rstd = rsqrtf(ss * (1.f / 128.f) + EPS);
;       const float* gn = hnorm + l * 512 + h * 128 + eg * 16;
;       bf16_t* rp = (bf16_t*)(ws + O_CR) + (size_t)(t0 + i) * 512 + h * 128 + eg * 16;
; #pragma unroll
;       for (int hh = 0; hh < 2; ++hh) { float rv[8]; unpack8(hh == 0 ? rraw0 : rraw1, rv);
; #pragma unroll
;           for (int e = 0; e < 8; ++e) rv[e] = ov[hh * 8 + e] * rstd * gn[hh * 8 + e] * siluf_(rv[e]);
;           if (dowrite) *(u32x4*)(rp + hh * 8) = pack8(rv); } }
	v_lshlrev_b32_e32 v58, 16, v5
	v_and_b32_e32 v5, 0xffff0000, v5
	v_mul_f32_e32 v56, 0xbfb8aa3b, v58
	v_mul_f32_e32 v57, 0xbfb8aa3b, v5
	v_exp_f32_e32 v56, v56
	v_exp_f32_e32 v57, v57
	ds_read_b128 v[20:23], v8 offset:64768
	ds_read_b128 v[16:19], v8 offset:64784
	ds_read_b128 v[12:15], v8 offset:64800
	ds_read_b128 v[8:11], v8 offset:64816
	global_load_dwordx4 v[48:51], v28, s[0:1] offset:16
	global_load_dwordx4 v[52:55], v28, s[0:1]
	global_load_dwordx4 v[134:137], v28, s[0:1] offset:48
	global_load_dwordx4 v[138:141], v28, s[0:1] offset:32
	v_rcp_f32_e32 v43, v6
	s_nop 0
	v_mul_f32_e32 v6, v42, v43
	v_pk_add_f32 v[56:57], v[56:57], 1.0 op_sel_hi:[1,0]
	s_waitcnt lgkmcnt(3)
	v_pk_mul_f32 v[42:43], v[22:23], v[22:23]
	s_waitcnt lgkmcnt(2)
	v_pk_mul_f32 v[38:39], v[16:17], v[16:17]
	v_pk_mul_f32 v[34:35], v[18:19], v[18:19]
	s_waitcnt lgkmcnt(0)
	v_pk_mul_f32 v[26:27], v[8:9], v[8:9]
	v_rcp_f32_e32 v59, v57
	s_nop 0
	v_mul_f32_e32 v57, v5, v59
	v_pk_mul_f32 v[24:25], v[10:11], v[10:11]
	v_lshlrev_b32_e32 v30, 2, v30
	v_lshlrev_b32_e32 v31, 2, v31
	v_lshlrev_b32_e32 v60, 16, v4
	v_and_b32_e32 v61, 0xffff0000, v4
	v_rcp_f32_e32 v5, v56
	s_nop 0
	v_mul_f32_e32 v56, v58, v5
	v_mul_f32_e32 v4, 0xbfb8aa3b, v60
	v_mul_f32_e32 v5, 0xbfb8aa3b, v61
	v_exp_f32_e32 v4, v4
	v_exp_f32_e32 v5, v5
	v_pk_mul_f32 v[58:59], v[20:21], v[20:21]
	s_add_i32 s98, s98, s97
	v_add_f32_e32 v58, v58, v59
	v_pk_add_f32 v[4:5], v[4:5], 1.0 op_sel_hi:[1,0]
	v_add_f32_e32 v42, v58, v42
	v_add_f32_e32 v42, v42, v43
	v_add_f32_e32 v38, v42, v38
	v_add_f32_e32 v38, v38, v39
	v_rcp_f32_e32 v62, v5
	s_nop 0
	v_mul_f32_e32 v5, v61, v62
	v_add_f32_e32 v34, v38, v34
	v_add_f32_e32 v34, v34, v35
	v_rcp_f32_e32 v61, v4
	s_nop 0
	v_mul_f32_e32 v4, v60, v61
	v_mul_f32_e32 v60, 0xbfb8aa3b, v37
	v_mul_f32_e32 v61, 0xbfb8aa3b, v41
	v_exp_f32_e32 v60, v60
	v_exp_f32_e32 v61, v61
	s_cmp_gt_i32 s98, s99
	v_pk_add_f32 v[60:61], v[60:61], 1.0 op_sel_hi:[1,0]
	s_nop 0
	s_nop 0
	v_rcp_f32_e32 v62, v61
	s_nop 0
	v_mul_f32_e32 v61, v41, v62
	v_lshlrev_b32_e32 v66, 16, v0
	v_mul_f32_e32 v0, 0xbfb8aa3b, v66
	v_exp_f32_e32 v0, v0
	v_rcp_f32_e32 v41, v60
	s_nop 0
	v_mul_f32_e32 v60, v37, v41
	v_lshlrev_b32_e32 v37, 16, v1
	v_and_b32_e32 v41, 0xffff0000, v1
	v_mul_f32_e32 v1, 0xbfb8aa3b, v67
	v_pk_mul_f32 v[64:65], v[12:13], v[12:13]
	v_exp_f32_e32 v1, v1
	v_add_f32_e32 v34, v34, v64
	v_pk_mul_f32 v[62:63], v[14:15], v[14:15]
	v_add_f32_e32 v34, v34, v65
	v_add_f32_e32 v34, v34, v62
	v_pk_add_f32 v[0:1], v[0:1], 1.0 op_sel_hi:[1,0]
	v_add_f32_e32 v34, v34, v63
	v_add_f32_e32 v26, v34, v26
	v_add_f32_e32 v26, v26, v27
	v_add_f32_e32 v24, v26, v24
	v_add_f32_e32 v24, v24, v25
	ds_bpermute_b32 v25, v29, v24
	s_waitcnt lgkmcnt(0)
	v_add_f32_e32 v24, v24, v25
	ds_bpermute_b32 v25, v30, v24
	v_rcp_f32_e32 v68, v1
	s_nop 0
	v_mul_f32_e32 v1, v67, v68
	s_waitcnt lgkmcnt(0)
	v_add_f32_e32 v24, v24, v25
	ds_bpermute_b32 v25, v31, v24
	s_waitcnt lgkmcnt(0)
	v_add_f32_e32 v24, v24, v25
	v_fmamk_f32 v24, v24, 0x3c000000, v216
	v_cmp_gt_f32_e32 vcc, s33, v24
	v_mul_f32_e32 v25, 0x4b800000, v24
	v_rcp_f32_e32 v67, v0
	s_nop 0
	v_mul_f32_e32 v0, v66, v67
	v_cndmask_b32_e32 v24, v24, v25, vcc
	v_rsq_f32_e32 v24, v24
	s_nop 0
	v_mul_f32_e32 v25, 0x45800000, v24
	v_cndmask_b32_e32 v24, v24, v25, vcc
	v_pk_mul_f32 v[20:21], v[20:21], v[24:25] op_sel_hi:[1,0]
	v_pk_mul_f32 v[16:17], v[16:17], v[24:25] op_sel_hi:[1,0]
	s_waitcnt vmcnt(0)
	v_pk_mul_f32 v[20:21], v[52:53], v[20:21]
	v_pk_mul_f32 v[16:17], v[48:49], v[16:17]
	v_pk_mul_f32 v[4:5], v[4:5], v[20:21]
	v_pk_mul_f32 v[20:21], v[22:23], v[24:25] op_sel_hi:[1,0]
	v_pk_mul_f32 v[6:7], v[6:7], v[16:17]
	v_pk_mul_f32 v[16:17], v[18:19], v[24:25] op_sel_hi:[1,0]
	v_pk_mul_f32 v[20:21], v[54:55], v[20:21]
	v_pk_mul_f32 v[16:17], v[50:51], v[16:17]
	v_pk_mul_f32 v[20:21], v[56:57], v[20:21]
	v_pk_mul_f32 v[16:17], v[60:61], v[16:17]
	v_cvt_pk_bf16_f32 v4, v4, v5
	v_cvt_pk_bf16_f32 v5, v20, v21
	v_cvt_pk_bf16_f32 v6, v6, v7
	v_cvt_pk_bf16_f32 v7, v16, v17
	global_store_dwordx4 v[32:33], v[4:7], off
	s_nop 1
	v_mov_b32_e32 v4, v134
	v_mov_b32_e32 v5, v135
	v_mov_b32_e32 v6, v136
	v_mov_b32_e32 v7, v137
	v_mov_b32_e32 v16, v138
	v_mov_b32_e32 v17, v139
	v_mov_b32_e32 v18, v140
	v_mov_b32_e32 v19, v141
	v_pk_mul_f32 v[12:13], v[12:13], v[24:25] op_sel_hi:[1,0]
	v_pk_mul_f32 v[14:15], v[14:15], v[24:25] op_sel_hi:[1,0]
	v_pk_mul_f32 v[8:9], v[8:9], v[24:25] op_sel_hi:[1,0]
	v_pk_mul_f32 v[12:13], v[12:13], v[16:17]
	s_nop 0
	v_pk_mul_f32 v[0:1], v[0:1], v[12:13]
	v_mul_f32_e32 v12, 0xbfb8aa3b, v37
	v_mul_f32_e32 v13, 0xbfb8aa3b, v41
	v_exp_f32_e32 v12, v12
	v_exp_f32_e32 v13, v13
	v_pk_mul_f32 v[14:15], v[14:15], v[18:19]
	v_pk_mul_f32 v[4:5], v[8:9], v[4:5]
	v_cvt_pk_bf16_f32 v0, v0, v1
	v_pk_add_f32 v[12:13], v[12:13], 1.0 op_sel_hi:[1,0]
	s_nop 0
	s_nop 0
	v_rcp_f32_e32 v16, v13
	s_nop 0
	v_mul_f32_e32 v13, v41, v16
	s_nop 0
	v_rcp_f32_e32 v16, v12
	s_nop 0
	v_mul_f32_e32 v12, v37, v16
	v_lshlrev_b32_e32 v16, 16, v2
	v_and_b32_e32 v2, 0xffff0000, v2
	v_pk_mul_f32 v[12:13], v[12:13], v[14:15]
	v_mul_f32_e32 v14, 0xbfb8aa3b, v16
	v_mul_f32_e32 v8, 0xbfb8aa3b, v2
	v_exp_f32_e32 v14, v14
	v_exp_f32_e32 v15, v8
	v_cvt_pk_bf16_f32 v1, v12, v13
	v_pk_add_f32 v[8:9], v[14:15], 1.0 op_sel_hi:[1,0]
	s_nop 0
	s_nop 0
	v_rcp_f32_e32 v14, v9
	s_nop 0
	v_mul_f32_e32 v9, v2, v14
	s_nop 0
	v_lshlrev_b32_e32 v14, 16, v3
	v_and_b32_e32 v15, 0xffff0000, v3
	v_rcp_f32_e32 v2, v8
	s_nop 0
	v_mul_f32_e32 v8, v16, v2
	v_mul_f32_e32 v2, 0xbfb8aa3b, v14
	v_mul_f32_e32 v3, 0xbfb8aa3b, v15
	v_exp_f32_e32 v2, v2
	v_exp_f32_e32 v3, v3
	v_pk_mul_f32 v[4:5], v[8:9], v[4:5]
	v_pk_mul_f32 v[8:9], v[10:11], v[24:25] op_sel_hi:[1,0]
	v_pk_add_f32 v[2:3], v[2:3], 1.0 op_sel_hi:[1,0]
	v_pk_mul_f32 v[6:7], v[8:9], v[6:7]
	s_nop 0
	v_rcp_f32_e32 v8, v3
	s_nop 0
	v_mul_f32_e32 v3, v15, v8
	s_nop 0
	v_rcp_f32_e32 v8, v2
	s_nop 0
	v_mul_f32_e32 v2, v14, v8
	v_pk_mul_f32 v[6:7], v[2:3], v[6:7]
	v_cvt_pk_bf16_f32 v2, v4, v5
	v_cvt_pk_bf16_f32 v3, v6, v7
	global_store_dwordx4 v[32:33], v[0:3], off offset:16
	s_barrier
	s_cbranch_scc0 .LBB0_394
